# out_proj epilogue software-pipelined over the two 128-row halves (row-sum exchange overlapped with streaming); plus unrolled silu staging in adaLN GEMV
# speedup vs baseline: 1.0123x; 1.0009x over previous
; #define LAS __attribute__((address_space(3)))
; __device__ __forceinline__ f32x4 ld_nt(const float* p) { return __builtin_nontemporal_load((const f32x4*)p); }
; __device__ __forceinline__ void gemv_item(LAS float* L, int item, const float* c, const float* c_ctx, const float* ada_w, const float* ada_b, float* mod) {
;     const int tid = threadIdx.x, wave = tid >> 6;
;     for (int i = tid; i < 3 * D; i += NTHREADS) { const int r = i / D, k = i % D; const float v = r < 2 ? c[r * D + k] : c_ctx[k]; L[i] = v / (1.f + expf(-v)); }
;     __syncthreads();
;     const int l8 = tid & 7, rs = tid >> 3, n0 = item * 32;
;     const float* wp = ada_w + n0 + 4 * l8;
;     f32x4 a0 = {0.f, 0.f, 0.f, 0.f}, a1 = a0, a2 = a0;
;     f32x4 wv[32];
; #pragma unroll
;     for (int i = 0; i < 32; ++i) wv[i] = ld_nt(wp + (size_t)(rs + 64 * i) * (3 * D));
.LBB0_70:
	s_and_b64 vcc, exec, s[4:5]
	s_cbranch_vccz .LBB0_78
	v_mov_b32_e32 v5, 0
	v_readlane_b32 s56, v254, 2
	v_lshlrev_b32_e32 v2, 2, v0
	v_mov_b32_e32 v3, v5
	v_readlane_b32 s58, v254, 4
	v_readlane_b32 s59, v254, 5
	v_add_u32_e32 v1, 0, v2
	v_readlane_b32 s62, v254, 8
	v_readlane_b32 s63, v254, 9
	v_readlane_b32 s64, v254, 10
	v_readlane_b32 s65, v254, 11
	v_lshl_add_u64 v[6:7], s[58:59], 0, v[2:3]
	s_mov_b64 s[4:5], 0
	s_movk_i32 s0, 0x1000
	s_mov_b32 s1, 0xbfb8aa3b
	s_mov_b32 s8, 0x42ce8ed0
	s_mov_b32 s9, 0xc2b17218
	v_mov_b32_e32 v3, 0x7f800000
	s_mov_b64 s[6:7], 0x800
	s_movk_i32 s10, 0x15ff
	v_mov_b32_e32 v8, v0
	v_readlane_b32 s57, v254, 3
	v_readlane_b32 s60, v254, 6
	v_readlane_b32 s61, v254, 7
	v_readlane_b32 s66, v254, 12
	v_readlane_b32 s67, v254, 13
	v_readlane_b32 s68, v254, 14
	v_readlane_b32 s69, v254, 15
	v_readlane_b32 s70, v254, 16
	v_readlane_b32 s71, v254, 17
	v_mov_b32_e32 v199, v1
	global_load_dword v200, v2, s[58:59]
	global_load_dword v201, v2, s[58:59] offset:2048
	s_add_u32 s98, s58, 0x1000
	s_addc_u32 s99, s59, 0
	s_add_u32 s100, s58, 0x2000
	s_addc_u32 s101, s59, 0
	global_load_dword v202, v2, s[98:99]
	global_load_dword v203, v2, s[98:99] offset:2048
	global_load_dword v204, v2, s[100:101]
	global_load_dword v205, v2, s[100:101] offset:2048
	s_add_u32 s98, s58, 0x3000
	s_addc_u32 s99, s59, 0
	s_add_u32 s100, s62, 0x1000
	s_addc_u32 s101, s63, 0
	global_load_dword v206, v2, s[98:99]
	global_load_dword v207, v2, s[98:99] offset:2048
	global_load_dword v208, v2, s[62:63]
	global_load_dword v209, v2, s[62:63] offset:2048
	global_load_dword v210, v2, s[100:101]
	global_load_dword v211, v2, s[100:101] offset:2048
	s_mov_b32 s98, 0xbfb8aa3b
	s_mov_b32 s99, 0x42ce8ed0
	s_mov_b32 s100, 0xc2b17218
	v_mov_b32_e32 v196, 0x7f800000
	s_lshl_b32 s4, s16, 5
	s_ashr_i32 s5, s4, 31
	s_lshl_b64 s[0:1], s[4:5], 2
	v_lshrrev_b32_e32 v1, 3, v0
	s_add_u32 s0, s64, s0
	v_and_b32_e32 v2, 28, v2
	s_addc_u32 s1, s65, s1
	v_lshlrev_b32_e32 v130, 2, v2
	v_mov_b32_e32 v131, 0
	v_mul_u32_u24_e32 v4, 0x1800, v1
	v_lshl_add_u64 v[2:3], s[0:1], 0, v[130:131]
	v_lshlrev_b32_e32 v4, 2, v4
	v_mov_b32_e32 v5, v131
	v_lshl_add_u64 v[2:3], v[2:3], 0, v[4:5]
	s_mov_b32 s0, 0x180000
	v_add_co_u32_e32 v4, vcc, s0, v2
	s_mov_b32 s0, 0x300000
	s_nop 0
	v_addc_co_u32_e32 v5, vcc, 0, v3, vcc
	global_load_dwordx4 v[126:129], v[2:3], off nt
	global_load_dwordx4 v[114:117], v[4:5], off nt
	v_add_co_u32_e32 v4, vcc, s0, v2
	s_mov_b32 s0, 0x480000
	s_nop 0
	v_addc_co_u32_e32 v5, vcc, 0, v3, vcc
	v_add_co_u32_e32 v6, vcc, s0, v2
	s_mov_b32 s0, 0x600000
	s_nop 0
	v_addc_co_u32_e32 v7, vcc, 0, v3, vcc
	global_load_dwordx4 v[122:125], v[4:5], off nt
	global_load_dwordx4 v[110:113], v[6:7], off nt
	v_add_co_u32_e32 v4, vcc, s0, v2
	s_mov_b32 s0, 0x780000
	s_nop 0
	v_addc_co_u32_e32 v5, vcc, 0, v3, vcc
	v_add_co_u32_e32 v6, vcc, s0, v2
	s_mov_b32 s0, 0x900000
	s_nop 0
	v_addc_co_u32_e32 v7, vcc, 0, v3, vcc
	global_load_dwordx4 v[118:121], v[4:5], off nt
	global_load_dwordx4 v[102:105], v[6:7], off nt
	v_add_co_u32_e32 v4, vcc, s0, v2
	s_mov_b32 s0, 0xa80000
	s_nop 0
	v_addc_co_u32_e32 v5, vcc, 0, v3, vcc
	v_add_co_u32_e32 v6, vcc, s0, v2
	s_mov_b32 s0, 0xc00000
	s_nop 0
	v_addc_co_u32_e32 v7, vcc, 0, v3, vcc
	global_load_dwordx4 v[106:109], v[4:5], off nt
	global_load_dwordx4 v[98:101], v[6:7], off nt
	v_add_co_u32_e32 v4, vcc, s0, v2
	s_mov_b32 s0, 0xd80000
	s_nop 0
	v_addc_co_u32_e32 v5, vcc, 0, v3, vcc
	v_add_co_u32_e32 v6, vcc, s0, v2
	s_mov_b32 s0, 0xf00000
	s_nop 0
	v_addc_co_u32_e32 v7, vcc, 0, v3, vcc
	global_load_dwordx4 v[94:97], v[4:5], off nt
	global_load_dwordx4 v[82:85], v[6:7], off nt
	v_add_co_u32_e32 v4, vcc, s0, v2
	s_mov_b32 s0, 0x1080000
	s_nop 0
	v_addc_co_u32_e32 v5, vcc, 0, v3, vcc
	v_add_co_u32_e32 v6, vcc, s0, v2
	s_mov_b32 s0, 0x1200000
	s_nop 0
	v_addc_co_u32_e32 v7, vcc, 0, v3, vcc
	global_load_dwordx4 v[90:93], v[4:5], off nt
	global_load_dwordx4 v[78:81], v[6:7], off nt
	v_add_co_u32_e32 v4, vcc, s0, v2
	s_mov_b32 s0, 0x1380000
	s_nop 0
	v_addc_co_u32_e32 v5, vcc, 0, v3, vcc
	v_add_co_u32_e32 v6, vcc, s0, v2
	s_mov_b32 s0, 0x1500000
	s_nop 0
	v_addc_co_u32_e32 v7, vcc, 0, v3, vcc
	global_load_dwordx4 v[86:89], v[4:5], off nt
	global_load_dwordx4 v[70:73], v[6:7], off nt
	v_add_co_u32_e32 v4, vcc, s0, v2
	s_mov_b32 s0, 0x1680000
	s_nop 0
	v_addc_co_u32_e32 v5, vcc, 0, v3, vcc
	v_add_co_u32_e32 v6, vcc, s0, v2
	s_mov_b32 s0, 0x1800000
	s_nop 0
	v_addc_co_u32_e32 v7, vcc, 0, v3, vcc
	global_load_dwordx4 v[74:77], v[4:5], off nt
	global_load_dwordx4 v[66:69], v[6:7], off nt
	v_add_co_u32_e32 v4, vcc, s0, v2
	s_mov_b32 s0, 0x1980000
	s_nop 0
	v_addc_co_u32_e32 v5, vcc, 0, v3, vcc
	v_add_co_u32_e32 v6, vcc, s0, v2
	s_mov_b32 s0, 0x1b00000
	s_nop 0
	v_addc_co_u32_e32 v7, vcc, 0, v3, vcc
	global_load_dwordx4 v[62:65], v[4:5], off nt
	global_load_dwordx4 v[50:53], v[6:7], off nt
	v_add_co_u32_e32 v4, vcc, s0, v2
	s_mov_b32 s0, 0x1c80000
	s_nop 0
	v_addc_co_u32_e32 v5, vcc, 0, v3, vcc
	v_add_co_u32_e32 v6, vcc, s0, v2
	s_mov_b32 s0, 0x1e00000
	s_nop 0
	v_addc_co_u32_e32 v7, vcc, 0, v3, vcc
	global_load_dwordx4 v[58:61], v[4:5], off nt
	global_load_dwordx4 v[46:49], v[6:7], off nt
	v_add_co_u32_e32 v4, vcc, s0, v2
	s_mov_b32 s0, 0x1f80000
	s_nop 0
	v_addc_co_u32_e32 v5, vcc, 0, v3, vcc
	v_add_co_u32_e32 v6, vcc, s0, v2
	s_mov_b32 s0, 0x2100000
	s_nop 0
	v_addc_co_u32_e32 v7, vcc, 0, v3, vcc
	global_load_dwordx4 v[54:57], v[4:5], off nt
	global_load_dwordx4 v[38:41], v[6:7], off nt
	v_add_co_u32_e32 v4, vcc, s0, v2
	s_mov_b32 s0, 0x2280000
	s_nop 0
	v_addc_co_u32_e32 v5, vcc, 0, v3, vcc
	v_add_co_u32_e32 v6, vcc, s0, v2
	s_mov_b32 s0, 0x2400000
	s_nop 0
	v_addc_co_u32_e32 v7, vcc, 0, v3, vcc
	global_load_dwordx4 v[42:45], v[4:5], off nt
	global_load_dwordx4 v[34:37], v[6:7], off nt
	v_add_co_u32_e32 v4, vcc, s0, v2
	s_mov_b32 s0, 0x2580000
	s_nop 0
	v_addc_co_u32_e32 v5, vcc, 0, v3, vcc
	v_add_co_u32_e32 v6, vcc, s0, v2
	s_mov_b32 s0, 0x2700000
	s_nop 0
	v_addc_co_u32_e32 v7, vcc, 0, v3, vcc
	global_load_dwordx4 v[30:33], v[4:5], off nt
	global_load_dwordx4 v[18:21], v[6:7], off nt
	v_add_co_u32_e32 v4, vcc, s0, v2
	s_mov_b32 s0, 0x2880000
	s_nop 0
	v_addc_co_u32_e32 v5, vcc, 0, v3, vcc
	v_add_co_u32_e32 v6, vcc, s0, v2
	s_mov_b32 s0, 0x2a00000
	s_nop 0
	v_addc_co_u32_e32 v7, vcc, 0, v3, vcc
	global_load_dwordx4 v[26:29], v[4:5], off nt
	global_load_dwordx4 v[14:17], v[6:7], off nt
	v_add_co_u32_e32 v4, vcc, s0, v2
	s_mov_b32 s0, 0x2b80000
	s_nop 0
	v_addc_co_u32_e32 v5, vcc, 0, v3, vcc
	v_add_co_u32_e32 v6, vcc, s0, v2
	s_mov_b32 s0, 0x2d00000
	s_nop 0
	v_addc_co_u32_e32 v7, vcc, 0, v3, vcc
	global_load_dwordx4 v[22:25], v[4:5], off nt
	s_nop 0
	global_load_dwordx4 v[6:9], v[6:7], off nt
	v_add_co_u32_e32 v4, vcc, s0, v2
	s_mov_b32 s0, 0x2e80000
	s_nop 0
	v_addc_co_u32_e32 v5, vcc, 0, v3, vcc
	v_add_co_u32_e32 v2, vcc, s0, v2
	s_nop 1
	v_addc_co_u32_e32 v3, vcc, 0, v3, vcc
	global_load_dwordx4 v[10:13], v[4:5], off nt
	s_nop 0
	global_load_dwordx4 v[2:5], v[2:3], off nt
	s_waitcnt vmcnt(43)
; __device__ __forceinline__ void gemv_item(LAS float* L, int item, const float* c, const float* c_ctx, const float* ada_w, const float* ada_b, float* mod) {
;     ...
;     for (int i = tid; i < 3 * D; i += NTHREADS) { const int r = i / D, k = i % D; const float v = r < 2 ? c[r * D + k] : c_ctx[k]; L[i] = v / (1.f + expf(-v)); }
	v_mul_f32_e32 v190, 0xbfb8aa3b, v200
	v_fma_f32 v191, v200, s98, -v190
	v_rndne_f32_e32 v192, v190
	v_fmac_f32_e32 v191, 0xb2a5705f, v200
	v_sub_f32_e32 v190, v190, v192
	v_add_f32_e32 v190, v190, v191
	v_cvt_i32_f32_e32 v192, v192
	v_exp_f32_e32 v190, v190
	v_cmp_nlt_f32_e32 vcc, s99, v200
	v_ldexp_f32 v190, v190, v192
	s_nop 0
	v_cndmask_b32_e32 v190, 0, v190, vcc
	v_cmp_ngt_f32_e32 vcc, s100, v200
	s_nop 1
	v_cndmask_b32_e32 v190, v196, v190, vcc
	v_add_f32_e32 v190, 1.0, v190
	v_div_scale_f32 v191, s[12:13], v190, v190, v200
	v_rcp_f32_e32 v192, v191
	v_div_scale_f32 v193, vcc, v200, v190, v200
	v_fma_f32 v194, -v191, v192, 1.0
	v_fmac_f32_e32 v192, v194, v192
	v_mul_f32_e32 v194, v193, v192
	v_fma_f32 v195, -v191, v194, v193
	v_fmac_f32_e32 v194, v195, v192
	v_fma_f32 v191, -v191, v194, v193
	v_div_fmas_f32 v191, v191, v192, v194
	v_div_fixup_f32 v200, v191, v190, v200
	ds_write_b32 v199, v200
	s_waitcnt vmcnt(42)
	v_mul_f32_e32 v190, 0xbfb8aa3b, v201
	v_fma_f32 v191, v201, s98, -v190
	v_rndne_f32_e32 v192, v190
	v_fmac_f32_e32 v191, 0xb2a5705f, v201
	v_sub_f32_e32 v190, v190, v192
	v_add_f32_e32 v190, v190, v191
	v_cvt_i32_f32_e32 v192, v192
	v_exp_f32_e32 v190, v190
	v_cmp_nlt_f32_e32 vcc, s99, v201
	v_ldexp_f32 v190, v190, v192
	s_nop 0
	v_cndmask_b32_e32 v190, 0, v190, vcc
	v_cmp_ngt_f32_e32 vcc, s100, v201
	s_nop 1
	v_cndmask_b32_e32 v190, v196, v190, vcc
	v_add_f32_e32 v190, 1.0, v190
	v_div_scale_f32 v191, s[12:13], v190, v190, v201
	v_rcp_f32_e32 v192, v191
	v_div_scale_f32 v193, vcc, v201, v190, v201
	v_fma_f32 v194, -v191, v192, 1.0
	v_fmac_f32_e32 v192, v194, v192
	v_mul_f32_e32 v194, v193, v192
	v_fma_f32 v195, -v191, v194, v193
	v_fmac_f32_e32 v194, v195, v192
	v_fma_f32 v191, -v191, v194, v193
	v_div_fmas_f32 v191, v191, v192, v194
	v_div_fixup_f32 v201, v191, v190, v201
	ds_write_b32 v199, v201 offset:2048
	s_waitcnt vmcnt(41)
	v_mul_f32_e32 v190, 0xbfb8aa3b, v202
	v_fma_f32 v191, v202, s98, -v190
	v_rndne_f32_e32 v192, v190
	v_fmac_f32_e32 v191, 0xb2a5705f, v202
	v_sub_f32_e32 v190, v190, v192
	v_add_f32_e32 v190, v190, v191
	v_cvt_i32_f32_e32 v192, v192
	v_exp_f32_e32 v190, v190
	v_cmp_nlt_f32_e32 vcc, s99, v202
	v_ldexp_f32 v190, v190, v192
	s_nop 0
	v_cndmask_b32_e32 v190, 0, v190, vcc
	v_cmp_ngt_f32_e32 vcc, s100, v202
	s_nop 1
	v_cndmask_b32_e32 v190, v196, v190, vcc
	v_add_f32_e32 v190, 1.0, v190
	v_div_scale_f32 v191, s[12:13], v190, v190, v202
	v_rcp_f32_e32 v192, v191
	v_div_scale_f32 v193, vcc, v202, v190, v202
	v_fma_f32 v194, -v191, v192, 1.0
	v_fmac_f32_e32 v192, v194, v192
	v_mul_f32_e32 v194, v193, v192
	v_fma_f32 v195, -v191, v194, v193
	v_fmac_f32_e32 v194, v195, v192
	v_fma_f32 v191, -v191, v194, v193
	v_div_fmas_f32 v191, v191, v192, v194
	v_div_fixup_f32 v202, v191, v190, v202
	ds_write_b32 v199, v202 offset:4096
	s_waitcnt vmcnt(40)
	v_mul_f32_e32 v190, 0xbfb8aa3b, v203
	v_fma_f32 v191, v203, s98, -v190
	v_rndne_f32_e32 v192, v190
	v_fmac_f32_e32 v191, 0xb2a5705f, v203
	v_sub_f32_e32 v190, v190, v192
	v_add_f32_e32 v190, v190, v191
	v_cvt_i32_f32_e32 v192, v192
	v_exp_f32_e32 v190, v190
	v_cmp_nlt_f32_e32 vcc, s99, v203
	v_ldexp_f32 v190, v190, v192
	s_nop 0
	v_cndmask_b32_e32 v190, 0, v190, vcc
	v_cmp_ngt_f32_e32 vcc, s100, v203
	s_nop 1
	v_cndmask_b32_e32 v190, v196, v190, vcc
	v_add_f32_e32 v190, 1.0, v190
	v_div_scale_f32 v191, s[12:13], v190, v190, v203
	v_rcp_f32_e32 v192, v191
	v_div_scale_f32 v193, vcc, v203, v190, v203
	v_fma_f32 v194, -v191, v192, 1.0
	v_fmac_f32_e32 v192, v194, v192
	v_mul_f32_e32 v194, v193, v192
	v_fma_f32 v195, -v191, v194, v193
	v_fmac_f32_e32 v194, v195, v192
	v_fma_f32 v191, -v191, v194, v193
	v_div_fmas_f32 v191, v191, v192, v194
	v_div_fixup_f32 v203, v191, v190, v203
	ds_write_b32 v199, v203 offset:6144
	s_waitcnt vmcnt(39)
	v_mul_f32_e32 v190, 0xbfb8aa3b, v204
	v_fma_f32 v191, v204, s98, -v190
	v_rndne_f32_e32 v192, v190
	v_fmac_f32_e32 v191, 0xb2a5705f, v204
	v_sub_f32_e32 v190, v190, v192
	v_add_f32_e32 v190, v190, v191
	v_cvt_i32_f32_e32 v192, v192
	v_exp_f32_e32 v190, v190
	v_cmp_nlt_f32_e32 vcc, s99, v204
	v_ldexp_f32 v190, v190, v192
	s_nop 0
	v_cndmask_b32_e32 v190, 0, v190, vcc
	v_cmp_ngt_f32_e32 vcc, s100, v204
	s_nop 1
	v_cndmask_b32_e32 v190, v196, v190, vcc
	v_add_f32_e32 v190, 1.0, v190
	v_div_scale_f32 v191, s[12:13], v190, v190, v204
	v_rcp_f32_e32 v192, v191
	v_div_scale_f32 v193, vcc, v204, v190, v204
	v_fma_f32 v194, -v191, v192, 1.0
	v_fmac_f32_e32 v192, v194, v192
	v_mul_f32_e32 v194, v193, v192
	v_fma_f32 v195, -v191, v194, v193
	v_fmac_f32_e32 v194, v195, v192
	v_fma_f32 v191, -v191, v194, v193
	v_div_fmas_f32 v191, v191, v192, v194
	v_div_fixup_f32 v204, v191, v190, v204
	ds_write_b32 v199, v204 offset:8192
	s_waitcnt vmcnt(38)
	v_mul_f32_e32 v190, 0xbfb8aa3b, v205
	v_fma_f32 v191, v205, s98, -v190
	v_rndne_f32_e32 v192, v190
	v_fmac_f32_e32 v191, 0xb2a5705f, v205
	v_sub_f32_e32 v190, v190, v192
	v_add_f32_e32 v190, v190, v191
	v_cvt_i32_f32_e32 v192, v192
	v_exp_f32_e32 v190, v190
	v_cmp_nlt_f32_e32 vcc, s99, v205
	v_ldexp_f32 v190, v190, v192
	s_nop 0
	v_cndmask_b32_e32 v190, 0, v190, vcc
	v_cmp_ngt_f32_e32 vcc, s100, v205
	s_nop 1
	v_cndmask_b32_e32 v190, v196, v190, vcc
	v_add_f32_e32 v190, 1.0, v190
	v_div_scale_f32 v191, s[12:13], v190, v190, v205
	v_rcp_f32_e32 v192, v191
	v_div_scale_f32 v193, vcc, v205, v190, v205
	v_fma_f32 v194, -v191, v192, 1.0
	v_fmac_f32_e32 v192, v194, v192
	v_mul_f32_e32 v194, v193, v192
	v_fma_f32 v195, -v191, v194, v193
	v_fmac_f32_e32 v194, v195, v192
	v_fma_f32 v191, -v191, v194, v193
	v_div_fmas_f32 v191, v191, v192, v194
	v_div_fixup_f32 v205, v191, v190, v205
	ds_write_b32 v199, v205 offset:10240
	s_waitcnt vmcnt(37)
; __device__ __forceinline__ void gemv_item(LAS float* L, int item, const float* c, const float* c_ctx, const float* ada_w, const float* ada_b, float* mod) {
;     ...
;     for (int i = tid; i < 3 * D; i += NTHREADS) { const int r = i / D, k = i % D; const float v = r < 2 ? c[r * D + k] : c_ctx[k]; L[i] = v / (1.f + expf(-v)); }
;     __syncthreads();
	v_mul_f32_e32 v190, 0xbfb8aa3b, v206
	v_fma_f32 v191, v206, s98, -v190
	v_rndne_f32_e32 v192, v190
	v_fmac_f32_e32 v191, 0xb2a5705f, v206
	v_sub_f32_e32 v190, v190, v192
	v_add_f32_e32 v190, v190, v191
	v_cvt_i32_f32_e32 v192, v192
	v_exp_f32_e32 v190, v190
	v_cmp_nlt_f32_e32 vcc, s99, v206
	v_ldexp_f32 v190, v190, v192
	s_nop 0
	v_cndmask_b32_e32 v190, 0, v190, vcc
	v_cmp_ngt_f32_e32 vcc, s100, v206
	s_nop 1
	v_cndmask_b32_e32 v190, v196, v190, vcc
	v_add_f32_e32 v190, 1.0, v190
	v_div_scale_f32 v191, s[12:13], v190, v190, v206
	v_rcp_f32_e32 v192, v191
	v_div_scale_f32 v193, vcc, v206, v190, v206
	v_fma_f32 v194, -v191, v192, 1.0
	v_fmac_f32_e32 v192, v194, v192
	v_mul_f32_e32 v194, v193, v192
	v_fma_f32 v195, -v191, v194, v193
	v_fmac_f32_e32 v194, v195, v192
	v_fma_f32 v191, -v191, v194, v193
	v_div_fmas_f32 v191, v191, v192, v194
	v_div_fixup_f32 v206, v191, v190, v206
	ds_write_b32 v199, v206 offset:12288
	s_waitcnt vmcnt(36)
	v_mul_f32_e32 v190, 0xbfb8aa3b, v207
	v_fma_f32 v191, v207, s98, -v190
	v_rndne_f32_e32 v192, v190
	v_fmac_f32_e32 v191, 0xb2a5705f, v207
	v_sub_f32_e32 v190, v190, v192
	v_add_f32_e32 v190, v190, v191
	v_cvt_i32_f32_e32 v192, v192
	v_exp_f32_e32 v190, v190
	v_cmp_nlt_f32_e32 vcc, s99, v207
	v_ldexp_f32 v190, v190, v192
	s_nop 0
	v_cndmask_b32_e32 v190, 0, v190, vcc
	v_cmp_ngt_f32_e32 vcc, s100, v207
	s_nop 1
	v_cndmask_b32_e32 v190, v196, v190, vcc
	v_add_f32_e32 v190, 1.0, v190
	v_div_scale_f32 v191, s[12:13], v190, v190, v207
	v_rcp_f32_e32 v192, v191
	v_div_scale_f32 v193, vcc, v207, v190, v207
	v_fma_f32 v194, -v191, v192, 1.0
	v_fmac_f32_e32 v192, v194, v192
	v_mul_f32_e32 v194, v193, v192
	v_fma_f32 v195, -v191, v194, v193
	v_fmac_f32_e32 v194, v195, v192
	v_fma_f32 v191, -v191, v194, v193
	v_div_fmas_f32 v191, v191, v192, v194
	v_div_fixup_f32 v207, v191, v190, v207
	ds_write_b32 v199, v207 offset:14336
	s_waitcnt vmcnt(35)
	v_mul_f32_e32 v190, 0xbfb8aa3b, v208
	v_fma_f32 v191, v208, s98, -v190
	v_rndne_f32_e32 v192, v190
	v_fmac_f32_e32 v191, 0xb2a5705f, v208
	v_sub_f32_e32 v190, v190, v192
	v_add_f32_e32 v190, v190, v191
	v_cvt_i32_f32_e32 v192, v192
	v_exp_f32_e32 v190, v190
	v_cmp_nlt_f32_e32 vcc, s99, v208
	v_ldexp_f32 v190, v190, v192
	s_nop 0
	v_cndmask_b32_e32 v190, 0, v190, vcc
	v_cmp_ngt_f32_e32 vcc, s100, v208
	s_nop 1
	v_cndmask_b32_e32 v190, v196, v190, vcc
	v_add_f32_e32 v190, 1.0, v190
	v_div_scale_f32 v191, s[12:13], v190, v190, v208
	v_rcp_f32_e32 v192, v191
	v_div_scale_f32 v193, vcc, v208, v190, v208
	v_fma_f32 v194, -v191, v192, 1.0
	v_fmac_f32_e32 v192, v194, v192
	v_mul_f32_e32 v194, v193, v192
	v_fma_f32 v195, -v191, v194, v193
	v_fmac_f32_e32 v194, v195, v192
	v_fma_f32 v191, -v191, v194, v193
	v_div_fmas_f32 v191, v191, v192, v194
	v_div_fixup_f32 v208, v191, v190, v208
	ds_write_b32 v199, v208 offset:16384
	s_waitcnt vmcnt(34)
	v_mul_f32_e32 v190, 0xbfb8aa3b, v209
	v_fma_f32 v191, v209, s98, -v190
	v_rndne_f32_e32 v192, v190
	v_fmac_f32_e32 v191, 0xb2a5705f, v209
	v_sub_f32_e32 v190, v190, v192
	v_add_f32_e32 v190, v190, v191
	v_cvt_i32_f32_e32 v192, v192
	v_exp_f32_e32 v190, v190
	v_cmp_nlt_f32_e32 vcc, s99, v209
	v_ldexp_f32 v190, v190, v192
	s_nop 0
	v_cndmask_b32_e32 v190, 0, v190, vcc
	v_cmp_ngt_f32_e32 vcc, s100, v209
	s_nop 1
	v_cndmask_b32_e32 v190, v196, v190, vcc
	v_add_f32_e32 v190, 1.0, v190
	v_div_scale_f32 v191, s[12:13], v190, v190, v209
	v_rcp_f32_e32 v192, v191
	v_div_scale_f32 v193, vcc, v209, v190, v209
	v_fma_f32 v194, -v191, v192, 1.0
	v_fmac_f32_e32 v192, v194, v192
	v_mul_f32_e32 v194, v193, v192
	v_fma_f32 v195, -v191, v194, v193
	v_fmac_f32_e32 v194, v195, v192
	v_fma_f32 v191, -v191, v194, v193
	v_div_fmas_f32 v191, v191, v192, v194
	v_div_fixup_f32 v209, v191, v190, v209
	ds_write_b32 v199, v209 offset:18432
	s_waitcnt vmcnt(33)
	v_mul_f32_e32 v190, 0xbfb8aa3b, v210
	v_fma_f32 v191, v210, s98, -v190
	v_rndne_f32_e32 v192, v190
	v_fmac_f32_e32 v191, 0xb2a5705f, v210
	v_sub_f32_e32 v190, v190, v192
	v_add_f32_e32 v190, v190, v191
	v_cvt_i32_f32_e32 v192, v192
	v_exp_f32_e32 v190, v190
	v_cmp_nlt_f32_e32 vcc, s99, v210
	v_ldexp_f32 v190, v190, v192
	s_nop 0
	v_cndmask_b32_e32 v190, 0, v190, vcc
	v_cmp_ngt_f32_e32 vcc, s100, v210
	s_nop 1
	v_cndmask_b32_e32 v190, v196, v190, vcc
	v_add_f32_e32 v190, 1.0, v190
	v_div_scale_f32 v191, s[12:13], v190, v190, v210
	v_rcp_f32_e32 v192, v191
	v_div_scale_f32 v193, vcc, v210, v190, v210
	v_fma_f32 v194, -v191, v192, 1.0
	v_fmac_f32_e32 v192, v194, v192
	v_mul_f32_e32 v194, v193, v192
	v_fma_f32 v195, -v191, v194, v193
	v_fmac_f32_e32 v194, v195, v192
	v_fma_f32 v191, -v191, v194, v193
	v_div_fmas_f32 v191, v191, v192, v194
	v_div_fixup_f32 v210, v191, v190, v210
	ds_write_b32 v199, v210 offset:20480
	s_waitcnt vmcnt(32)
	v_mul_f32_e32 v190, 0xbfb8aa3b, v211
	v_fma_f32 v191, v211, s98, -v190
	v_rndne_f32_e32 v192, v190
	v_fmac_f32_e32 v191, 0xb2a5705f, v211
	v_sub_f32_e32 v190, v190, v192
	v_add_f32_e32 v190, v190, v191
	v_cvt_i32_f32_e32 v192, v192
	v_exp_f32_e32 v190, v190
	v_cmp_nlt_f32_e32 vcc, s99, v211
	v_ldexp_f32 v190, v190, v192
	s_nop 0
	v_cndmask_b32_e32 v190, 0, v190, vcc
	v_cmp_ngt_f32_e32 vcc, s100, v211
	s_nop 1
	v_cndmask_b32_e32 v190, v196, v190, vcc
	v_add_f32_e32 v190, 1.0, v190
	v_div_scale_f32 v191, s[12:13], v190, v190, v211
	v_rcp_f32_e32 v192, v191
	v_div_scale_f32 v193, vcc, v211, v190, v211
	v_fma_f32 v194, -v191, v192, 1.0
	v_fmac_f32_e32 v192, v194, v192
	v_mul_f32_e32 v194, v193, v192
	v_fma_f32 v195, -v191, v194, v193
	v_fmac_f32_e32 v194, v195, v192
	v_fma_f32 v191, -v191, v194, v193
	v_div_fmas_f32 v191, v191, v192, v194
	v_div_fixup_f32 v211, v191, v190, v211
	ds_write_b32 v199, v211 offset:22528
	s_waitcnt lgkmcnt(0)
	s_barrier
; __device__ __forceinline__ void gemv_item(LAS float* L, int item, const float* c, const float* c_ctx, const float* ada_w, const float* ada_b, float* mod) {
;     ...
; #pragma unroll
;     for (int i = 0; i < 32; ++i) { const int k = rs + 64 * i; a0 += L[k] * wv[i]; a1 += L[D + k] * wv[i]; a2 += L[2 * D + k] * wv[i]; }
	v_lshl_add_u32 v1, v1, 2, 0
	ds_read2st64_b32 v[132:133], v1 offset1:1
	ds_read2st64_b32 v[134:135], v1 offset0:32 offset1:33
	ds_read2st64_b32 v[136:137], v1 offset0:2 offset1:3
	ds_read2st64_b32 v[138:139], v1 offset0:4 offset1:5
	ds_read2st64_b32 v[140:141], v1 offset0:6 offset1:7
	ds_read2st64_b32 v[146:147], v1 offset0:34 offset1:35
	ds_read2st64_b32 v[148:149], v1 offset0:36 offset1:37
	ds_read2st64_b32 v[150:151], v1 offset0:38 offset1:39
	ds_read2st64_b32 v[154:155], v1 offset0:64 offset1:65
	s_waitcnt vmcnt(31) lgkmcnt(8)
	v_pk_fma_f32 v[142:143], v[128:129], v[132:133], 0 op_sel_hi:[1,0,0]
	v_pk_fma_f32 v[144:145], v[126:127], v[132:133], 0 op_sel_hi:[1,0,0]
	s_waitcnt lgkmcnt(7)
	v_pk_fma_f32 v[152:153], v[128:129], v[134:135], 0 op_sel_hi:[1,0,0]
	v_pk_fma_f32 v[156:157], v[126:127], v[134:135], 0 op_sel_hi:[1,0,0]
	ds_read2st64_b32 v[158:159], v1 offset0:66 offset1:67
	ds_read2st64_b32 v[160:161], v1 offset0:68 offset1:69
	ds_read2st64_b32 v[162:163], v1 offset0:70 offset1:71
	v_mov_b32_e32 v132, v133
	v_mov_b32_e32 v134, v135
	s_waitcnt lgkmcnt(3)
	v_pk_fma_f32 v[126:127], v[126:127], v[154:155], 0 op_sel_hi:[1,0,0]
	s_waitcnt vmcnt(30)
	v_pk_fma_f32 v[142:143], v[116:117], v[132:133], v[142:143] op_sel_hi:[1,0,1]
	v_pk_fma_f32 v[132:133], v[114:115], v[132:133], v[144:145] op_sel_hi:[1,0,1]
	v_pk_fma_f32 v[144:145], v[116:117], v[134:135], v[152:153] op_sel_hi:[1,0,1]
	v_mov_b32_e32 v152, v155
	v_pk_fma_f32 v[128:129], v[128:129], v[154:155], 0 op_sel_hi:[1,0,0]
	v_pk_fma_f32 v[134:135], v[114:115], v[134:135], v[156:157] op_sel_hi:[1,0,1]
	v_pk_fma_f32 v[114:115], v[114:115], v[152:153], v[126:127] op_sel_hi:[1,0,1]
	v_pk_fma_f32 v[116:117], v[116:117], v[152:153], v[128:129] op_sel_hi:[1,0,1]
	s_waitcnt vmcnt(29)
	v_pk_fma_f32 v[126:127], v[124:125], v[136:137], v[142:143] op_sel_hi:[1,0,1]
	v_pk_fma_f32 v[128:129], v[122:123], v[136:137], v[132:133] op_sel_hi:[1,0,1]
	v_pk_fma_f32 v[134:135], v[122:123], v[146:147], v[134:135] op_sel_hi:[1,0,1]
	s_waitcnt lgkmcnt(2)
	v_pk_fma_f32 v[114:115], v[122:123], v[158:159], v[114:115] op_sel_hi:[1,0,1]
	v_mov_b32_e32 v122, v137
	v_pk_fma_f32 v[132:133], v[124:125], v[146:147], v[144:145] op_sel_hi:[1,0,1]
	v_pk_fma_f32 v[116:117], v[124:125], v[158:159], v[116:117] op_sel_hi:[1,0,1]
	s_waitcnt vmcnt(28)
	v_pk_fma_f32 v[124:125], v[112:113], v[122:123], v[126:127] op_sel_hi:[1,0,1]
	v_mov_b32_e32 v126, v147
	v_pk_fma_f32 v[122:123], v[110:111], v[122:123], v[128:129] op_sel_hi:[1,0,1]
	v_pk_fma_f32 v[128:129], v[112:113], v[126:127], v[132:133] op_sel_hi:[1,0,1]
	v_mov_b32_e32 v132, v159
	v_pk_fma_f32 v[126:127], v[110:111], v[126:127], v[134:135] op_sel_hi:[1,0,1]
	v_pk_fma_f32 v[110:111], v[110:111], v[132:133], v[114:115] op_sel_hi:[1,0,1]
	v_pk_fma_f32 v[112:113], v[112:113], v[132:133], v[116:117] op_sel_hi:[1,0,1]
	s_waitcnt vmcnt(27)
	v_pk_fma_f32 v[114:115], v[120:121], v[138:139], v[124:125] op_sel_hi:[1,0,1]
	v_pk_fma_f32 v[116:117], v[118:119], v[138:139], v[122:123] op_sel_hi:[1,0,1]
	v_pk_fma_f32 v[124:125], v[118:119], v[148:149], v[126:127] op_sel_hi:[1,0,1]
	s_waitcnt lgkmcnt(1)
	v_pk_fma_f32 v[110:111], v[118:119], v[160:161], v[110:111] op_sel_hi:[1,0,1]
	v_mov_b32_e32 v118, v139
	v_pk_fma_f32 v[122:123], v[120:121], v[148:149], v[128:129] op_sel_hi:[1,0,1]
	s_waitcnt vmcnt(26)
	v_pk_fma_f32 v[114:115], v[104:105], v[118:119], v[114:115] op_sel_hi:[1,0,1]
	v_pk_fma_f32 v[116:117], v[102:103], v[118:119], v[116:117] op_sel_hi:[1,0,1]
	v_mov_b32_e32 v118, v149
	v_pk_fma_f32 v[112:113], v[120:121], v[160:161], v[112:113] op_sel_hi:[1,0,1]
	v_pk_fma_f32 v[120:121], v[104:105], v[118:119], v[122:123] op_sel_hi:[1,0,1]
	v_mov_b32_e32 v122, v161
	v_pk_fma_f32 v[118:119], v[102:103], v[118:119], v[124:125] op_sel_hi:[1,0,1]
	v_pk_fma_f32 v[102:103], v[102:103], v[122:123], v[110:111] op_sel_hi:[1,0,1]
	v_pk_fma_f32 v[104:105], v[104:105], v[122:123], v[112:113] op_sel_hi:[1,0,1]
	s_waitcnt vmcnt(25)
	v_pk_fma_f32 v[110:111], v[108:109], v[140:141], v[114:115] op_sel_hi:[1,0,1]
	v_pk_fma_f32 v[112:113], v[106:107], v[140:141], v[116:117] op_sel_hi:[1,0,1]
	v_pk_fma_f32 v[116:117], v[106:107], v[150:151], v[118:119] op_sel_hi:[1,0,1]
	s_waitcnt lgkmcnt(0)
	v_pk_fma_f32 v[102:103], v[106:107], v[162:163], v[102:103] op_sel_hi:[1,0,1]
	v_mov_b32_e32 v106, v141
	v_pk_fma_f32 v[114:115], v[108:109], v[150:151], v[120:121] op_sel_hi:[1,0,1]
	v_pk_fma_f32 v[104:105], v[108:109], v[162:163], v[104:105] op_sel_hi:[1,0,1]
	s_waitcnt vmcnt(24)
	v_pk_fma_f32 v[108:109], v[100:101], v[106:107], v[110:111] op_sel_hi:[1,0,1]
	v_mov_b32_e32 v110, v151
	v_pk_fma_f32 v[106:107], v[98:99], v[106:107], v[112:113] op_sel_hi:[1,0,1]
	v_pk_fma_f32 v[112:113], v[100:101], v[110:111], v[114:115] op_sel_hi:[1,0,1]
	v_mov_b32_e32 v114, v163
	v_pk_fma_f32 v[110:111], v[98:99], v[110:111], v[116:117] op_sel_hi:[1,0,1]
	v_pk_fma_f32 v[100:101], v[100:101], v[114:115], v[104:105] op_sel_hi:[1,0,1]
	ds_read2st64_b32 v[104:105], v1 offset0:8 offset1:9
	v_pk_fma_f32 v[98:99], v[98:99], v[114:115], v[102:103] op_sel_hi:[1,0,1]
	ds_read2st64_b32 v[102:103], v1 offset0:10 offset1:11
	ds_read2st64_b32 v[114:115], v1 offset0:12 offset1:13
	ds_read2st64_b32 v[116:117], v1 offset0:14 offset1:15
	ds_read2st64_b32 v[118:119], v1 offset0:40 offset1:41
	ds_read2st64_b32 v[120:121], v1 offset0:42 offset1:43
	ds_read2st64_b32 v[122:123], v1 offset0:44 offset1:45
	ds_read2st64_b32 v[124:125], v1 offset0:46 offset1:47
	ds_read2st64_b32 v[126:127], v1 offset0:72 offset1:73
	s_waitcnt vmcnt(23) lgkmcnt(8)
	v_pk_fma_f32 v[108:109], v[96:97], v[104:105], v[108:109] op_sel_hi:[1,0,1]
	v_pk_fma_f32 v[106:107], v[94:95], v[104:105], v[106:107] op_sel_hi:[1,0,1]
	s_waitcnt lgkmcnt(4)
; __device__ __forceinline__ void gemv_item(LAS float* L, int item, const float* c, const float* c_ctx, const float* ada_w, const float* ada_b, float* mod) {
;     ...
;     for (int i = 0; i < 32; ++i) { const int k = rs + 64 * i; a0 += L[k] * wv[i]; a1 += L[D + k] * wv[i]; a2 += L[2 * D + k] * wv[i]; }
	v_pk_fma_f32 v[110:111], v[94:95], v[118:119], v[110:111] op_sel_hi:[1,0,1]
	ds_read2st64_b32 v[128:129], v1 offset0:74 offset1:75
	ds_read2st64_b32 v[132:133], v1 offset0:76 offset1:77
	ds_read2st64_b32 v[134:135], v1 offset0:78 offset1:79
	s_waitcnt lgkmcnt(3)
	v_pk_fma_f32 v[94:95], v[94:95], v[126:127], v[98:99] op_sel_hi:[1,0,1]
	v_mov_b32_e32 v98, v105
	v_pk_fma_f32 v[112:113], v[96:97], v[118:119], v[112:113] op_sel_hi:[1,0,1]
	v_pk_fma_f32 v[96:97], v[96:97], v[126:127], v[100:101] op_sel_hi:[1,0,1]
	s_waitcnt vmcnt(22)
	v_pk_fma_f32 v[100:101], v[84:85], v[98:99], v[108:109] op_sel_hi:[1,0,1]
	v_mov_b32_e32 v104, v119
	v_mov_b32_e32 v108, v127
	v_pk_fma_f32 v[98:99], v[82:83], v[98:99], v[106:107] op_sel_hi:[1,0,1]
	v_pk_fma_f32 v[106:107], v[84:85], v[104:105], v[112:113] op_sel_hi:[1,0,1]
	v_pk_fma_f32 v[104:105], v[82:83], v[104:105], v[110:111] op_sel_hi:[1,0,1]
	v_pk_fma_f32 v[82:83], v[82:83], v[108:109], v[94:95] op_sel_hi:[1,0,1]
	v_pk_fma_f32 v[84:85], v[84:85], v[108:109], v[96:97] op_sel_hi:[1,0,1]
	s_waitcnt vmcnt(21)
	v_pk_fma_f32 v[94:95], v[92:93], v[102:103], v[100:101] op_sel_hi:[1,0,1]
	v_pk_fma_f32 v[96:97], v[90:91], v[102:103], v[98:99] op_sel_hi:[1,0,1]
	v_pk_fma_f32 v[100:101], v[90:91], v[120:121], v[104:105] op_sel_hi:[1,0,1]
	s_waitcnt lgkmcnt(2)
	v_pk_fma_f32 v[82:83], v[90:91], v[128:129], v[82:83] op_sel_hi:[1,0,1]
	v_mov_b32_e32 v90, v103
	v_pk_fma_f32 v[98:99], v[92:93], v[120:121], v[106:107] op_sel_hi:[1,0,1]
	v_pk_fma_f32 v[84:85], v[92:93], v[128:129], v[84:85] op_sel_hi:[1,0,1]
	s_waitcnt vmcnt(20)
	v_pk_fma_f32 v[92:93], v[80:81], v[90:91], v[94:95] op_sel_hi:[1,0,1]
	v_mov_b32_e32 v94, v121
	v_pk_fma_f32 v[90:91], v[78:79], v[90:91], v[96:97] op_sel_hi:[1,0,1]
	v_pk_fma_f32 v[96:97], v[80:81], v[94:95], v[98:99] op_sel_hi:[1,0,1]
	v_mov_b32_e32 v98, v129
	v_pk_fma_f32 v[94:95], v[78:79], v[94:95], v[100:101] op_sel_hi:[1,0,1]
	v_pk_fma_f32 v[78:79], v[78:79], v[98:99], v[82:83] op_sel_hi:[1,0,1]
	v_pk_fma_f32 v[80:81], v[80:81], v[98:99], v[84:85] op_sel_hi:[1,0,1]
	s_waitcnt vmcnt(19)
	v_pk_fma_f32 v[82:83], v[88:89], v[114:115], v[92:93] op_sel_hi:[1,0,1]
	v_pk_fma_f32 v[84:85], v[86:87], v[114:115], v[90:91] op_sel_hi:[1,0,1]
	v_pk_fma_f32 v[92:93], v[86:87], v[122:123], v[94:95] op_sel_hi:[1,0,1]
	s_waitcnt lgkmcnt(1)
	v_pk_fma_f32 v[78:79], v[86:87], v[132:133], v[78:79] op_sel_hi:[1,0,1]
	v_mov_b32_e32 v86, v115
	v_pk_fma_f32 v[90:91], v[88:89], v[122:123], v[96:97] op_sel_hi:[1,0,1]
	s_waitcnt vmcnt(18)
	v_pk_fma_f32 v[82:83], v[72:73], v[86:87], v[82:83] op_sel_hi:[1,0,1]
	v_pk_fma_f32 v[84:85], v[70:71], v[86:87], v[84:85] op_sel_hi:[1,0,1]
	v_mov_b32_e32 v86, v123
	v_pk_fma_f32 v[80:81], v[88:89], v[132:133], v[80:81] op_sel_hi:[1,0,1]
	v_pk_fma_f32 v[88:89], v[72:73], v[86:87], v[90:91] op_sel_hi:[1,0,1]
	v_mov_b32_e32 v90, v133
	v_pk_fma_f32 v[86:87], v[70:71], v[86:87], v[92:93] op_sel_hi:[1,0,1]
	v_pk_fma_f32 v[70:71], v[70:71], v[90:91], v[78:79] op_sel_hi:[1,0,1]
	v_pk_fma_f32 v[72:73], v[72:73], v[90:91], v[80:81] op_sel_hi:[1,0,1]
	s_waitcnt vmcnt(17)
	v_pk_fma_f32 v[78:79], v[76:77], v[116:117], v[82:83] op_sel_hi:[1,0,1]
	v_pk_fma_f32 v[80:81], v[74:75], v[116:117], v[84:85] op_sel_hi:[1,0,1]
	v_pk_fma_f32 v[84:85], v[74:75], v[124:125], v[86:87] op_sel_hi:[1,0,1]
	s_waitcnt lgkmcnt(0)
	v_pk_fma_f32 v[70:71], v[74:75], v[134:135], v[70:71] op_sel_hi:[1,0,1]
	v_mov_b32_e32 v74, v117
	v_pk_fma_f32 v[82:83], v[76:77], v[124:125], v[88:89] op_sel_hi:[1,0,1]
	v_pk_fma_f32 v[72:73], v[76:77], v[134:135], v[72:73] op_sel_hi:[1,0,1]
	s_waitcnt vmcnt(16)
	v_pk_fma_f32 v[76:77], v[68:69], v[74:75], v[78:79] op_sel_hi:[1,0,1]
	v_mov_b32_e32 v78, v125
	v_pk_fma_f32 v[74:75], v[66:67], v[74:75], v[80:81] op_sel_hi:[1,0,1]
	v_pk_fma_f32 v[80:81], v[68:69], v[78:79], v[82:83] op_sel_hi:[1,0,1]
	v_mov_b32_e32 v82, v135
	v_pk_fma_f32 v[78:79], v[66:67], v[78:79], v[84:85] op_sel_hi:[1,0,1]
	v_pk_fma_f32 v[68:69], v[68:69], v[82:83], v[72:73] op_sel_hi:[1,0,1]
	ds_read2st64_b32 v[72:73], v1 offset0:16 offset1:17
	v_pk_fma_f32 v[66:67], v[66:67], v[82:83], v[70:71] op_sel_hi:[1,0,1]
	ds_read2st64_b32 v[70:71], v1 offset0:18 offset1:19
	ds_read2st64_b32 v[82:83], v1 offset0:20 offset1:21
	ds_read2st64_b32 v[84:85], v1 offset0:22 offset1:23
	ds_read2st64_b32 v[86:87], v1 offset0:48 offset1:49
	ds_read2st64_b32 v[88:89], v1 offset0:50 offset1:51
	ds_read2st64_b32 v[90:91], v1 offset0:52 offset1:53
	ds_read2st64_b32 v[92:93], v1 offset0:54 offset1:55
	ds_read2st64_b32 v[94:95], v1 offset0:80 offset1:81
	s_waitcnt vmcnt(15) lgkmcnt(8)
	v_pk_fma_f32 v[76:77], v[64:65], v[72:73], v[76:77] op_sel_hi:[1,0,1]
	v_pk_fma_f32 v[74:75], v[62:63], v[72:73], v[74:75] op_sel_hi:[1,0,1]
	s_waitcnt lgkmcnt(4)
	v_pk_fma_f32 v[78:79], v[62:63], v[86:87], v[78:79] op_sel_hi:[1,0,1]
	ds_read2st64_b32 v[96:97], v1 offset0:82 offset1:83
	ds_read2st64_b32 v[98:99], v1 offset0:84 offset1:85
	ds_read2st64_b32 v[100:101], v1 offset0:86 offset1:87
	s_waitcnt lgkmcnt(3)
	v_pk_fma_f32 v[62:63], v[62:63], v[94:95], v[66:67] op_sel_hi:[1,0,1]
	v_mov_b32_e32 v66, v73
	v_pk_fma_f32 v[80:81], v[64:65], v[86:87], v[80:81] op_sel_hi:[1,0,1]
	v_pk_fma_f32 v[64:65], v[64:65], v[94:95], v[68:69] op_sel_hi:[1,0,1]
	s_waitcnt vmcnt(14)
	v_pk_fma_f32 v[68:69], v[52:53], v[66:67], v[76:77] op_sel_hi:[1,0,1]
	v_mov_b32_e32 v72, v87
	v_mov_b32_e32 v76, v95
	v_pk_fma_f32 v[66:67], v[50:51], v[66:67], v[74:75] op_sel_hi:[1,0,1]
	v_pk_fma_f32 v[74:75], v[52:53], v[72:73], v[80:81] op_sel_hi:[1,0,1]
	v_pk_fma_f32 v[72:73], v[50:51], v[72:73], v[78:79] op_sel_hi:[1,0,1]
	v_pk_fma_f32 v[50:51], v[50:51], v[76:77], v[62:63] op_sel_hi:[1,0,1]
	v_pk_fma_f32 v[52:53], v[52:53], v[76:77], v[64:65] op_sel_hi:[1,0,1]
	s_waitcnt vmcnt(13)
; __device__ __forceinline__ void gemv_item(LAS float* L, int item, const float* c, const float* c_ctx, const float* ada_w, const float* ada_b, float* mod) {
;     ...
;     for (int i = 0; i < 32; ++i) { const int k = rs + 64 * i; a0 += L[k] * wv[i]; a1 += L[D + k] * wv[i]; a2 += L[2 * D + k] * wv[i]; }
	v_pk_fma_f32 v[62:63], v[60:61], v[70:71], v[68:69] op_sel_hi:[1,0,1]
	v_pk_fma_f32 v[64:65], v[58:59], v[70:71], v[66:67] op_sel_hi:[1,0,1]
	v_pk_fma_f32 v[68:69], v[58:59], v[88:89], v[72:73] op_sel_hi:[1,0,1]
	s_waitcnt lgkmcnt(2)
	v_pk_fma_f32 v[50:51], v[58:59], v[96:97], v[50:51] op_sel_hi:[1,0,1]
	v_mov_b32_e32 v58, v71
	v_pk_fma_f32 v[66:67], v[60:61], v[88:89], v[74:75] op_sel_hi:[1,0,1]
	v_pk_fma_f32 v[52:53], v[60:61], v[96:97], v[52:53] op_sel_hi:[1,0,1]
	s_waitcnt vmcnt(12)
	v_pk_fma_f32 v[60:61], v[48:49], v[58:59], v[62:63] op_sel_hi:[1,0,1]
	v_mov_b32_e32 v62, v89
	v_pk_fma_f32 v[58:59], v[46:47], v[58:59], v[64:65] op_sel_hi:[1,0,1]
	v_pk_fma_f32 v[64:65], v[48:49], v[62:63], v[66:67] op_sel_hi:[1,0,1]
	v_mov_b32_e32 v66, v97
	v_pk_fma_f32 v[62:63], v[46:47], v[62:63], v[68:69] op_sel_hi:[1,0,1]
	v_pk_fma_f32 v[46:47], v[46:47], v[66:67], v[50:51] op_sel_hi:[1,0,1]
	v_pk_fma_f32 v[48:49], v[48:49], v[66:67], v[52:53] op_sel_hi:[1,0,1]
	s_waitcnt vmcnt(11)
	v_pk_fma_f32 v[50:51], v[56:57], v[82:83], v[60:61] op_sel_hi:[1,0,1]
	v_pk_fma_f32 v[52:53], v[54:55], v[82:83], v[58:59] op_sel_hi:[1,0,1]
	v_pk_fma_f32 v[60:61], v[54:55], v[90:91], v[62:63] op_sel_hi:[1,0,1]
	s_waitcnt lgkmcnt(1)
	v_pk_fma_f32 v[46:47], v[54:55], v[98:99], v[46:47] op_sel_hi:[1,0,1]
	v_mov_b32_e32 v54, v83
	v_pk_fma_f32 v[58:59], v[56:57], v[90:91], v[64:65] op_sel_hi:[1,0,1]
	s_waitcnt vmcnt(10)
	v_pk_fma_f32 v[50:51], v[40:41], v[54:55], v[50:51] op_sel_hi:[1,0,1]
	v_pk_fma_f32 v[52:53], v[38:39], v[54:55], v[52:53] op_sel_hi:[1,0,1]
	v_mov_b32_e32 v54, v91
	v_pk_fma_f32 v[48:49], v[56:57], v[98:99], v[48:49] op_sel_hi:[1,0,1]
	v_pk_fma_f32 v[56:57], v[40:41], v[54:55], v[58:59] op_sel_hi:[1,0,1]
	v_mov_b32_e32 v58, v99
	v_pk_fma_f32 v[54:55], v[38:39], v[54:55], v[60:61] op_sel_hi:[1,0,1]
	v_pk_fma_f32 v[38:39], v[38:39], v[58:59], v[46:47] op_sel_hi:[1,0,1]
	v_pk_fma_f32 v[40:41], v[40:41], v[58:59], v[48:49] op_sel_hi:[1,0,1]
	s_waitcnt vmcnt(9)
	v_pk_fma_f32 v[46:47], v[44:45], v[84:85], v[50:51] op_sel_hi:[1,0,1]
	v_pk_fma_f32 v[48:49], v[42:43], v[84:85], v[52:53] op_sel_hi:[1,0,1]
	v_pk_fma_f32 v[52:53], v[42:43], v[92:93], v[54:55] op_sel_hi:[1,0,1]
	s_waitcnt lgkmcnt(0)
	v_pk_fma_f32 v[38:39], v[42:43], v[100:101], v[38:39] op_sel_hi:[1,0,1]
	v_mov_b32_e32 v42, v85
	v_pk_fma_f32 v[50:51], v[44:45], v[92:93], v[56:57] op_sel_hi:[1,0,1]
	v_pk_fma_f32 v[40:41], v[44:45], v[100:101], v[40:41] op_sel_hi:[1,0,1]
	s_waitcnt vmcnt(8)
	v_pk_fma_f32 v[44:45], v[36:37], v[42:43], v[46:47] op_sel_hi:[1,0,1]
	v_mov_b32_e32 v46, v93
	v_pk_fma_f32 v[42:43], v[34:35], v[42:43], v[48:49] op_sel_hi:[1,0,1]
	v_pk_fma_f32 v[48:49], v[36:37], v[46:47], v[50:51] op_sel_hi:[1,0,1]
	v_mov_b32_e32 v50, v101
	v_pk_fma_f32 v[46:47], v[34:35], v[46:47], v[52:53] op_sel_hi:[1,0,1]
	v_pk_fma_f32 v[36:37], v[36:37], v[50:51], v[40:41] op_sel_hi:[1,0,1]
	ds_read2st64_b32 v[40:41], v1 offset0:24 offset1:25
	v_pk_fma_f32 v[34:35], v[34:35], v[50:51], v[38:39] op_sel_hi:[1,0,1]
	ds_read2st64_b32 v[38:39], v1 offset0:26 offset1:27
	ds_read2st64_b32 v[50:51], v1 offset0:28 offset1:29
	ds_read2st64_b32 v[52:53], v1 offset0:30 offset1:31
	ds_read2st64_b32 v[54:55], v1 offset0:56 offset1:57
	ds_read2st64_b32 v[56:57], v1 offset0:58 offset1:59
	ds_read2st64_b32 v[58:59], v1 offset0:60 offset1:61
	ds_read2st64_b32 v[60:61], v1 offset0:62 offset1:63
	ds_read2st64_b32 v[62:63], v1 offset0:88 offset1:89
	s_waitcnt vmcnt(7) lgkmcnt(8)
	v_pk_fma_f32 v[44:45], v[32:33], v[40:41], v[44:45] op_sel_hi:[1,0,1]
	v_pk_fma_f32 v[42:43], v[30:31], v[40:41], v[42:43] op_sel_hi:[1,0,1]
	s_waitcnt lgkmcnt(4)
	v_pk_fma_f32 v[46:47], v[30:31], v[54:55], v[46:47] op_sel_hi:[1,0,1]
	ds_read2st64_b32 v[64:65], v1 offset0:90 offset1:91
	ds_read2st64_b32 v[66:67], v1 offset0:92 offset1:93
	ds_read2st64_b32 v[68:69], v1 offset0:94 offset1:95
	s_waitcnt lgkmcnt(3)
	v_pk_fma_f32 v[30:31], v[30:31], v[62:63], v[34:35] op_sel_hi:[1,0,1]
	v_mov_b32_e32 v34, v41
	v_pk_fma_f32 v[48:49], v[32:33], v[54:55], v[48:49] op_sel_hi:[1,0,1]
	v_pk_fma_f32 v[32:33], v[32:33], v[62:63], v[36:37] op_sel_hi:[1,0,1]
	s_waitcnt vmcnt(6)
	v_pk_fma_f32 v[36:37], v[20:21], v[34:35], v[44:45] op_sel_hi:[1,0,1]
	v_mov_b32_e32 v40, v55
	v_mov_b32_e32 v44, v63
	v_pk_fma_f32 v[34:35], v[18:19], v[34:35], v[42:43] op_sel_hi:[1,0,1]
	v_pk_fma_f32 v[42:43], v[20:21], v[40:41], v[48:49] op_sel_hi:[1,0,1]
	v_pk_fma_f32 v[40:41], v[18:19], v[40:41], v[46:47] op_sel_hi:[1,0,1]
	v_pk_fma_f32 v[18:19], v[18:19], v[44:45], v[30:31] op_sel_hi:[1,0,1]
	v_pk_fma_f32 v[20:21], v[20:21], v[44:45], v[32:33] op_sel_hi:[1,0,1]
	s_waitcnt vmcnt(5)
	v_pk_fma_f32 v[30:31], v[28:29], v[38:39], v[36:37] op_sel_hi:[1,0,1]
	v_pk_fma_f32 v[32:33], v[26:27], v[38:39], v[34:35] op_sel_hi:[1,0,1]
	v_pk_fma_f32 v[36:37], v[26:27], v[56:57], v[40:41] op_sel_hi:[1,0,1]
	s_waitcnt lgkmcnt(2)
	v_pk_fma_f32 v[18:19], v[26:27], v[64:65], v[18:19] op_sel_hi:[1,0,1]
	v_mov_b32_e32 v26, v39
	v_pk_fma_f32 v[34:35], v[28:29], v[56:57], v[42:43] op_sel_hi:[1,0,1]
	v_pk_fma_f32 v[20:21], v[28:29], v[64:65], v[20:21] op_sel_hi:[1,0,1]
	s_waitcnt vmcnt(4)
; #define LAS __attribute__((address_space(3)))
; __device__ __forceinline__ void gemv_item(LAS float* L, int item, const float* c, const float* c_ctx, const float* ada_w, const float* ada_b, float* mod) {
;     ...
;     for (int i = 0; i < 32; ++i) { const int k = rs + 64 * i; a0 += L[k] * wv[i]; a1 += L[D + k] * wv[i]; a2 += L[2 * D + k] * wv[i]; }
; #pragma unroll
;     for (int e = 0; e < 4; ++e) {
; #pragma unroll
;         for (int o = 8; o < 64; o <<= 1) { a0[e] += __shfl_xor(a0[e], o); a1[e] += __shfl_xor(a1[e], o); a2[e] += __shfl_xor(a2[e], o); } }
;     LAS float* red = L + 3 * D;
;     if ((tid & 63) < 8) {
; #pragma unroll
;         for (int e = 0; e < 4; ++e) { red[wave * 96 + l8 * 4 + e] = a0[e]; red[wave * 96 + 32 + l8 * 4 + e] = a1[e]; red[wave * 96 + 64 + l8 * 4 + e] = a2[e]; } }
	v_pk_fma_f32 v[28:29], v[16:17], v[26:27], v[30:31] op_sel_hi:[1,0,1]
	v_mov_b32_e32 v30, v57
	v_pk_fma_f32 v[26:27], v[14:15], v[26:27], v[32:33] op_sel_hi:[1,0,1]
	v_pk_fma_f32 v[32:33], v[16:17], v[30:31], v[34:35] op_sel_hi:[1,0,1]
	v_mov_b32_e32 v34, v65
	v_pk_fma_f32 v[30:31], v[14:15], v[30:31], v[36:37] op_sel_hi:[1,0,1]
	v_pk_fma_f32 v[14:15], v[14:15], v[34:35], v[18:19] op_sel_hi:[1,0,1]
	v_pk_fma_f32 v[16:17], v[16:17], v[34:35], v[20:21] op_sel_hi:[1,0,1]
	s_waitcnt vmcnt(3)
	v_pk_fma_f32 v[18:19], v[24:25], v[50:51], v[28:29] op_sel_hi:[1,0,1]
	v_pk_fma_f32 v[20:21], v[22:23], v[50:51], v[26:27] op_sel_hi:[1,0,1]
	v_pk_fma_f32 v[28:29], v[22:23], v[58:59], v[30:31] op_sel_hi:[1,0,1]
	s_waitcnt lgkmcnt(1)
	v_pk_fma_f32 v[14:15], v[22:23], v[66:67], v[14:15] op_sel_hi:[1,0,1]
	v_mov_b32_e32 v22, v51
	v_pk_fma_f32 v[26:27], v[24:25], v[58:59], v[32:33] op_sel_hi:[1,0,1]
	s_waitcnt vmcnt(2)
	v_pk_fma_f32 v[18:19], v[8:9], v[22:23], v[18:19] op_sel_hi:[1,0,1]
	v_pk_fma_f32 v[20:21], v[6:7], v[22:23], v[20:21] op_sel_hi:[1,0,1]
	v_mov_b32_e32 v22, v59
	v_pk_fma_f32 v[16:17], v[24:25], v[66:67], v[16:17] op_sel_hi:[1,0,1]
	v_pk_fma_f32 v[24:25], v[8:9], v[22:23], v[26:27] op_sel_hi:[1,0,1]
	v_mov_b32_e32 v26, v67
	v_pk_fma_f32 v[22:23], v[6:7], v[22:23], v[28:29] op_sel_hi:[1,0,1]
	v_pk_fma_f32 v[8:9], v[8:9], v[26:27], v[16:17] op_sel_hi:[1,0,1]
	v_pk_fma_f32 v[6:7], v[6:7], v[26:27], v[14:15] op_sel_hi:[1,0,1]
	s_waitcnt vmcnt(1)
	v_pk_fma_f32 v[14:15], v[12:13], v[52:53], v[18:19] op_sel_hi:[1,0,1]
	v_pk_fma_f32 v[16:17], v[10:11], v[52:53], v[20:21] op_sel_hi:[1,0,1]
	v_pk_fma_f32 v[18:19], v[12:13], v[60:61], v[24:25] op_sel_hi:[1,0,1]
	v_pk_fma_f32 v[20:21], v[10:11], v[60:61], v[22:23] op_sel_hi:[1,0,1]
	s_waitcnt lgkmcnt(0)
	v_pk_fma_f32 v[8:9], v[12:13], v[68:69], v[8:9] op_sel_hi:[1,0,1]
	v_pk_fma_f32 v[6:7], v[10:11], v[68:69], v[6:7] op_sel_hi:[1,0,1]
	v_mov_b32_e32 v10, v53
	v_mov_b32_e32 v12, v61
	v_mbcnt_lo_u32_b32 v1, -1, 0
	s_waitcnt vmcnt(0)
	v_pk_fma_f32 v[14:15], v[4:5], v[10:11], v[14:15] op_sel_hi:[1,0,1]
	v_pk_fma_f32 v[10:11], v[2:3], v[10:11], v[16:17] op_sel_hi:[1,0,1]
	v_pk_fma_f32 v[16:17], v[4:5], v[12:13], v[18:19] op_sel_hi:[1,0,1]
	v_mov_b32_e32 v18, v69
	v_mbcnt_hi_u32_b32 v1, -1, v1
	v_pk_fma_f32 v[12:13], v[2:3], v[12:13], v[20:21] op_sel_hi:[1,0,1]
	v_pk_fma_f32 v[20:21], v[4:5], v[18:19], v[8:9] op_sel_hi:[1,0,1]
	v_and_b32_e32 v4, 64, v1
	v_pk_fma_f32 v[2:3], v[2:3], v[18:19], v[6:7] op_sel_hi:[1,0,1]
	v_add_u32_e32 v7, 64, v4
	v_xor_b32_e32 v4, 8, v1
	v_cmp_lt_i32_e32 vcc, v4, v7
	v_xor_b32_e32 v5, 16, v1
	v_xor_b32_e32 v9, 32, v1
	v_cndmask_b32_e32 v4, v1, v4, vcc
	v_cmp_lt_i32_e32 vcc, v5, v7
	v_lshlrev_b32_e32 v26, 2, v4
	ds_bpermute_b32 v4, v26, v10
	v_cndmask_b32_e32 v5, v1, v5, vcc
	v_cmp_lt_i32_e32 vcc, v9, v7
	ds_bpermute_b32 v6, v26, v12
	ds_bpermute_b32 v8, v26, v2
	v_lshlrev_b32_e32 v31, 2, v5
	ds_bpermute_b32 v5, v26, v11
	v_cndmask_b32_e32 v1, v1, v9, vcc
	ds_bpermute_b32 v7, v26, v13
	ds_bpermute_b32 v9, v26, v3
	v_lshlrev_b32_e32 v1, 2, v1
	s_waitcnt lgkmcnt(2)
	v_pk_add_f32 v[4:5], v[10:11], v[4:5]
	ds_bpermute_b32 v10, v31, v4
	s_waitcnt lgkmcnt(2)
	v_pk_add_f32 v[12:13], v[12:13], v[6:7]
	s_waitcnt lgkmcnt(1)
	v_pk_add_f32 v[22:23], v[2:3], v[8:9]
	ds_bpermute_b32 v11, v31, v5
	ds_bpermute_b32 v18, v31, v12
	ds_bpermute_b32 v19, v31, v13
	ds_bpermute_b32 v24, v31, v22
	ds_bpermute_b32 v25, v31, v23
	s_waitcnt lgkmcnt(4)
	v_pk_add_f32 v[2:3], v[4:5], v[10:11]
	ds_bpermute_b32 v6, v1, v2
	s_waitcnt lgkmcnt(3)
	v_pk_add_f32 v[4:5], v[12:13], v[18:19]
	ds_bpermute_b32 v18, v26, v14
	s_waitcnt lgkmcnt(2)
	v_pk_add_f32 v[10:11], v[22:23], v[24:25]
	ds_bpermute_b32 v19, v26, v15
	ds_bpermute_b32 v22, v26, v16
	ds_bpermute_b32 v24, v26, v20
	ds_bpermute_b32 v23, v26, v17
	ds_bpermute_b32 v25, v26, v21
	s_waitcnt lgkmcnt(4)
	v_pk_add_f32 v[14:15], v[14:15], v[18:19]
	ds_bpermute_b32 v18, v31, v14
	ds_bpermute_b32 v19, v31, v15
	s_waitcnt lgkmcnt(3)
	v_pk_add_f32 v[16:17], v[16:17], v[22:23]
	s_waitcnt lgkmcnt(2)
	v_pk_add_f32 v[28:29], v[20:21], v[24:25]
	ds_bpermute_b32 v26, v31, v16
	ds_bpermute_b32 v27, v31, v17
	ds_bpermute_b32 v30, v31, v28
	ds_bpermute_b32 v31, v31, v29
	s_waitcnt lgkmcnt(4)
	v_pk_add_f32 v[22:23], v[14:15], v[18:19]
	ds_bpermute_b32 v8, v1, v4
	s_waitcnt lgkmcnt(3)
	v_pk_add_f32 v[18:19], v[16:17], v[26:27]
	ds_bpermute_b32 v12, v1, v10
	s_waitcnt lgkmcnt(2)
	v_pk_add_f32 v[14:15], v[28:29], v[30:31]
	ds_bpermute_b32 v7, v1, v3
	ds_bpermute_b32 v9, v1, v5
	ds_bpermute_b32 v13, v1, v11
	ds_bpermute_b32 v24, v1, v22
	ds_bpermute_b32 v20, v1, v18
	ds_bpermute_b32 v16, v1, v14
	ds_bpermute_b32 v25, v1, v23
	ds_bpermute_b32 v21, v1, v19
	ds_bpermute_b32 v17, v1, v15
	v_and_b32_e32 v1, 56, v0
	v_cmp_eq_u32_e32 vcc, 0, v1
	s_and_saveexec_b64 s[6:7], vcc
	s_cbranch_execz .LBB0_75
	v_lshrrev_b32_e32 v1, 6, v0
	v_mul_u32_u24_e32 v1, 0x180, v1
	v_add3_u32 v1, 0, v1, v130
	s_waitcnt lgkmcnt(8)
	v_pk_add_f32 v[2:3], v[2:3], v[6:7]
	s_waitcnt lgkmcnt(7)
	v_pk_add_f32 v[6:7], v[4:5], v[8:9]
	s_waitcnt lgkmcnt(6)
	v_pk_add_f32 v[10:11], v[10:11], v[12:13]
	s_waitcnt lgkmcnt(2)
	v_pk_add_f32 v[4:5], v[22:23], v[24:25]
	s_waitcnt lgkmcnt(1)
	v_pk_add_f32 v[8:9], v[18:19], v[20:21]
	s_waitcnt lgkmcnt(0)
	v_pk_add_f32 v[12:13], v[14:15], v[16:17]
	ds_write_b128 v1, v[2:5] offset:24576
	ds_write_b128 v1, v[6:9] offset:24704
	ds_write_b128 v1, v[10:13] offset:24832

; __device__ __forceinline__ f32x4 ld_nt(const float* p) { return __builtin_nontemporal_load((const f32x4*)p); }
;     __device__ __forceinline__ void operator()(AccRef acc, const Unit& u, int wr, int wc, int fr, int fq) const {
;         int row0 = u.pm * 256 + wr * 64 + fr; asm volatile("" : "+v"(row0)); int col0 = u.pn * 256 + wc * 32 + 8 * fq; asm volatile("" : "+v"(col0));
;         const float* gate = mod + (size_t)(u.pm >= 32 ? 1 : 0) * 3 * D + 2 * D + col0;
;         f32x4 gv[2][2];
; #pragma unroll
;         for (int bj = 0; bj < 2; ++bj)
; #pragma unroll
;             for (int n = 0; n < 2; ++n) gv[bj][n] = *(const f32x4*)(gate + bj * HALF + n * 4);
; #pragma unroll
;         for (int ai = 0; ai < 2; ++ai)
; #pragma unroll
;             for (int mp = 0; mp < 2; ++mp) { f32x4 xv[2][2][2];
; #pragma unroll
;                 for (int mm = 0; mm < 2; ++mm)
; #pragma unroll
;                     for (int bj = 0; bj < 2; ++bj)
; #pragma unroll
;                         for (int n = 0; n < 2; ++n) xv[mm][bj][n] = ld_nt(x + (size_t)(row0 + ai * HALF + (mp * 2 + mm) * 16) * D + col0 + bj * HALF + n * 4);
;                 __builtin_amdgcn_sched_barrier(0);
; #pragma unroll
;                 for (int mm = 0; mm < 2; ++mm) { const int m = mp * 2 + mm; const int row = row0 + ai * HALF + m * 16; const size_t o = (size_t)row * D + col0; float ss = 0.f;
; #pragma unroll
;                     for (int bj = 0; bj < 2; ++bj) { const f32x4 r0 = xv[mm][bj][0] + gv[bj][0] * acc[ai][bj][m][0], r1 = xv[mm][bj][1] + gv[bj][1] * acc[ai][bj][m][1];
.LBB0_1154:
	v_lshl_add_u32 v172, s58, 8, v178
	v_lshl_or_b32 v170, s22, 8, v180
	v_readlane_b32 s80, v254, 2
	v_readlane_b32 s81, v254, 3
	v_lshlrev_b32_e32 v173, 13, v172
	v_lshlrev_b32_e32 v187, 7, v172
	v_lshlrev_b32_e32 v171, 2, v170
	v_lshl_add_u32 v173, v170, 2, v173
	s_cmp_gt_i32 s58, 31
	s_cselect_b32 s18, 0x6000, 0
	s_add_u32 s92, s50, s18
	s_addc_u32 s93, s51, 0
	s_add_u32 s92, s92, 0x104000
	s_addc_u32 s93, s93, 0
	s_lshl_b32 s18, s22, 2
	s_add_u32 s18, s18, s72
	s_lshl_b32 s18, s18, 2
	s_add_u32 s88, s26, s18
	s_addc_u32 s89, s27, 0
	v_xor_b32_e32 v186, 16, v184
	v_xor_b32_e32 v185, 32, v184
	v_lshrrev_b32_e32 v174, 4, v184
	v_lshlrev_b32_e32 v186, 2, v186
	v_lshlrev_b32_e32 v185, 2, v185
	v_lshl_add_u32 v174, v174, 5, v187
	s_mov_b32 s94, 0x3a000000
	s_mov_b32 s95, 0x358637bd
	s_mov_b64 s[82:83], s[48:49]
	s_lshr_b32 s59, s65, 10
	global_load_dwordx4 v[120:123], v171, s[92:93]
	global_load_dwordx4 v[112:115], v171, s[92:93] offset:16
	global_load_dwordx4 v[108:111], v171, s[92:93] offset:512
	global_load_dwordx4 v[104:107], v171, s[92:93] offset:528
	global_load_dwordx4 v[144:147], v171, s[46:47]
	global_load_dwordx4 v[148:151], v171, s[46:47] offset:16
	global_load_dwordx4 v[152:155], v171, s[46:47] offset:512
	global_load_dwordx4 v[156:159], v171, s[46:47] offset:528
	s_mov_b64 s[84:85], s[80:81]
	global_load_dwordx4 v[188:191], v173, s[84:85] nt
	global_load_dwordx4 v[192:195], v173, s[84:85] offset:16 nt
	global_load_dwordx4 v[196:199], v173, s[84:85] offset:512 nt
	global_load_dwordx4 v[200:203], v173, s[84:85] offset:528 nt
	s_add_u32 s84, s80, 0x20000
	s_addc_u32 s85, s81, 0
	global_load_dwordx4 v[214:217], v173, s[84:85] nt
	global_load_dwordx4 v[218:221], v173, s[84:85] offset:16 nt
	global_load_dwordx4 v[222:225], v173, s[84:85] offset:512 nt
	global_load_dwordx4 v[226:229], v173, s[84:85] offset:528 nt
	s_add_u32 s84, s80, 0x40000
	s_addc_u32 s85, s81, 0
	global_load_dwordx4 v[230:233], v173, s[84:85] nt
	global_load_dwordx4 v[234:237], v173, s[84:85] offset:16 nt
	global_load_dwordx4 v[238:241], v173, s[84:85] offset:512 nt
	global_load_dwordx4 v[242:245], v173, s[84:85] offset:528 nt
	s_waitcnt vmcnt(8)
	v_pk_fma_f32 v[140:141], v[140:141], v[120:121], v[188:189]
	v_pk_fma_f32 v[142:143], v[142:143], v[122:123], v[190:191]
	v_pk_fma_f32 v[136:137], v[136:137], v[112:113], v[192:193]
	v_pk_fma_f32 v[138:139], v[138:139], v[114:115], v[194:195]
	v_pk_fma_f32 v[132:133], v[132:133], v[108:109], v[196:197]
	v_pk_fma_f32 v[134:135], v[134:135], v[110:111], v[198:199]
	v_pk_fma_f32 v[128:129], v[128:129], v[104:105], v[200:201]
	v_pk_fma_f32 v[130:131], v[130:131], v[106:107], v[202:203]
	s_add_u32 s84, s80, 0x60000
	s_addc_u32 s85, s81, 0
	global_load_dwordx4 v[188:191], v173, s[84:85] nt
	global_load_dwordx4 v[192:195], v173, s[84:85] offset:16 nt
	global_load_dwordx4 v[196:199], v173, s[84:85] offset:512 nt
	global_load_dwordx4 v[200:203], v173, s[84:85] offset:528 nt
	v_pk_mul_f32 v[176:177], v[140:141], v[140:141]
	v_pk_fma_f32 v[176:177], v[142:143], v[142:143], v[176:177]
	v_pk_fma_f32 v[176:177], v[136:137], v[136:137], v[176:177]
	v_pk_fma_f32 v[176:177], v[138:139], v[138:139], v[176:177]
	v_pk_fma_f32 v[176:177], v[132:133], v[132:133], v[176:177]
	v_pk_fma_f32 v[176:177], v[134:135], v[134:135], v[176:177]
	v_pk_fma_f32 v[176:177], v[128:129], v[128:129], v[176:177]
	v_pk_fma_f32 v[176:177], v[130:131], v[130:131], v[176:177]
	v_add_f32_e32 v204, v176, v177
	s_waitcnt vmcnt(8)
	v_pk_fma_f32 v[124:125], v[124:125], v[120:121], v[214:215]
	v_pk_fma_f32 v[126:127], v[126:127], v[122:123], v[216:217]
	v_pk_fma_f32 v[116:117], v[116:117], v[112:113], v[218:219]
	v_pk_fma_f32 v[118:119], v[118:119], v[114:115], v[220:221]
	v_pk_fma_f32 v[100:101], v[100:101], v[108:109], v[222:223]
	v_pk_fma_f32 v[102:103], v[102:103], v[110:111], v[224:225]
	v_pk_fma_f32 v[96:97], v[96:97], v[104:105], v[226:227]
	v_pk_fma_f32 v[98:99], v[98:99], v[106:107], v[228:229]
	s_add_u32 s84, s80, 0x100000
	s_addc_u32 s85, s81, 0
	global_load_dwordx4 v[214:217], v173, s[84:85] nt
	global_load_dwordx4 v[218:221], v173, s[84:85] offset:16 nt
	global_load_dwordx4 v[222:225], v173, s[84:85] offset:512 nt
	global_load_dwordx4 v[226:229], v173, s[84:85] offset:528 nt
	v_pk_mul_f32 v[176:177], v[124:125], v[124:125]
	v_pk_fma_f32 v[176:177], v[126:127], v[126:127], v[176:177]
	v_pk_fma_f32 v[176:177], v[116:117], v[116:117], v[176:177]
	v_pk_fma_f32 v[176:177], v[118:119], v[118:119], v[176:177]
	v_pk_fma_f32 v[176:177], v[100:101], v[100:101], v[176:177]
	v_pk_fma_f32 v[176:177], v[102:103], v[102:103], v[176:177]
	v_pk_fma_f32 v[176:177], v[96:97], v[96:97], v[176:177]
	v_pk_fma_f32 v[176:177], v[98:99], v[98:99], v[176:177]
	v_add_f32_e32 v205, v176, v177
	s_waitcnt vmcnt(8)
	v_pk_fma_f32 v[92:93], v[92:93], v[120:121], v[230:231]
	v_pk_fma_f32 v[94:95], v[94:95], v[122:123], v[232:233]
	v_pk_fma_f32 v[88:89], v[88:89], v[112:113], v[234:235]
	v_pk_fma_f32 v[90:91], v[90:91], v[114:115], v[236:237]
	v_pk_fma_f32 v[84:85], v[84:85], v[108:109], v[238:239]
	v_pk_fma_f32 v[86:87], v[86:87], v[110:111], v[240:241]
	v_pk_fma_f32 v[80:81], v[80:81], v[104:105], v[242:243]
	v_pk_fma_f32 v[82:83], v[82:83], v[106:107], v[244:245]
	s_add_u32 s84, s80, 0x120000
	s_addc_u32 s85, s81, 0
	global_load_dwordx4 v[230:233], v173, s[84:85] nt
	global_load_dwordx4 v[234:237], v173, s[84:85] offset:16 nt
	global_load_dwordx4 v[238:241], v173, s[84:85] offset:512 nt
	global_load_dwordx4 v[242:245], v173, s[84:85] offset:528 nt
	v_pk_mul_f32 v[176:177], v[92:93], v[92:93]
	v_pk_fma_f32 v[176:177], v[94:95], v[94:95], v[176:177]
	v_pk_fma_f32 v[176:177], v[88:89], v[88:89], v[176:177]
	v_pk_fma_f32 v[176:177], v[90:91], v[90:91], v[176:177]
	v_pk_fma_f32 v[176:177], v[84:85], v[84:85], v[176:177]
	v_pk_fma_f32 v[176:177], v[86:87], v[86:87], v[176:177]
	v_pk_fma_f32 v[176:177], v[80:81], v[80:81], v[176:177]
	v_pk_fma_f32 v[176:177], v[82:83], v[82:83], v[176:177]
	v_add_f32_e32 v206, v176, v177
	s_waitcnt vmcnt(8)
; __device__ __forceinline__ u32x4 pack8h(const f32x4 v0, const f32x4 v1) { u32x4 w; w.x = pk_h16(v0[0], v0[1]); w.y = pk_h16(v0[2], v0[3]); w.z = pk_h16(v1[0], v1[1]); w.w = pk_h16(v1[2], v1[3]); return w; }
;     __device__ __forceinline__ void operator()(AccRef acc, const Unit& u, int wr, int wc, int fr, int fq) const {
;     ...
;                 for (int mm = 0; mm < 2; ++mm) { const int m = mp * 2 + mm; const int row = row0 + ai * HALF + m * 16; const size_t o = (size_t)row * D + col0; float ss = 0.f;
; #pragma unroll
;                     for (int bj = 0; bj < 2; ++bj) { const f32x4 r0 = xv[mm][bj][0] + gv[bj][0] * acc[ai][bj][m][0], r1 = xv[mm][bj][1] + gv[bj][1] * acc[ai][bj][m][1];
;                         *(u32x4*)(xo + o + bj * HALF) = pack8h(r0, r1);
;                         ss += ((r0[0] * r0[0] + r0[1] * r0[1]) + (r0[2] * r0[2] + r0[3] * r0[3])) + ((r1[0] * r1[0] + r1[1] * r1[1]) + (r1[2] * r1[2] + r1[3] * r1[3])); }
;                     ss += __shfl_xor(ss, 16); ss += __shfl_xor(ss, 32);
;                     if (fq == 0) rowss[(size_t)row * 32 + u.pn * 4 + wc] = ss; } }
	v_pk_fma_f32 v[76:77], v[76:77], v[120:121], v[188:189]
	v_pk_fma_f32 v[78:79], v[78:79], v[122:123], v[190:191]
	v_pk_fma_f32 v[72:73], v[72:73], v[112:113], v[192:193]
	v_pk_fma_f32 v[74:75], v[74:75], v[114:115], v[194:195]
	v_pk_fma_f32 v[68:69], v[68:69], v[108:109], v[196:197]
	v_pk_fma_f32 v[70:71], v[70:71], v[110:111], v[198:199]
	v_pk_fma_f32 v[64:65], v[64:65], v[104:105], v[200:201]
	v_pk_fma_f32 v[66:67], v[66:67], v[106:107], v[202:203]
	s_add_u32 s84, s80, 0x140000
	s_addc_u32 s85, s81, 0
	global_load_dwordx4 v[188:191], v173, s[84:85] nt
	global_load_dwordx4 v[192:195], v173, s[84:85] offset:16 nt
	global_load_dwordx4 v[196:199], v173, s[84:85] offset:512 nt
	global_load_dwordx4 v[200:203], v173, s[84:85] offset:528 nt
	v_pk_mul_f32 v[176:177], v[76:77], v[76:77]
	v_pk_fma_f32 v[176:177], v[78:79], v[78:79], v[176:177]
	v_pk_fma_f32 v[176:177], v[72:73], v[72:73], v[176:177]
	v_pk_fma_f32 v[176:177], v[74:75], v[74:75], v[176:177]
	v_pk_fma_f32 v[176:177], v[68:69], v[68:69], v[176:177]
	v_pk_fma_f32 v[176:177], v[70:71], v[70:71], v[176:177]
	v_pk_fma_f32 v[176:177], v[64:65], v[64:65], v[176:177]
	v_pk_fma_f32 v[176:177], v[66:67], v[66:67], v[176:177]
	v_add_f32_e32 v207, v176, v177
	ds_bpermute_b32 v246, v186, v204
	ds_bpermute_b32 v247, v186, v205
	ds_bpermute_b32 v248, v186, v206
	ds_bpermute_b32 v249, v186, v207
	s_waitcnt lgkmcnt(0)
	v_pk_add_f32 v[204:205], v[204:205], v[246:247]
	v_pk_add_f32 v[206:207], v[206:207], v[248:249]
	ds_bpermute_b32 v246, v185, v204
	ds_bpermute_b32 v247, v185, v205
	ds_bpermute_b32 v248, v185, v206
	ds_bpermute_b32 v249, v185, v207
	s_waitcnt lgkmcnt(0)
	v_pk_add_f32 v[204:205], v[204:205], v[246:247]
	v_pk_add_f32 v[206:207], v[206:207], v[248:249]
	s_and_saveexec_b64 s[20:21], s[2:3]
	s_mov_b64 s[90:91], s[88:89]
	global_store_dword v187, v204, s[90:91] sc0 sc1
	s_add_u32 s90, s88, 0x800
	s_addc_u32 s91, s89, 0
	global_store_dword v187, v205, s[90:91] sc0 sc1
	s_add_u32 s90, s88, 0x1000
	s_addc_u32 s91, s89, 0
	global_store_dword v187, v206, s[90:91] sc0 sc1
	s_add_u32 s90, s88, 0x1800
	s_addc_u32 s91, s89, 0
	global_store_dword v187, v207, s[90:91] sc0 sc1
	s_or_b64 exec, exec, s[20:21]
	s_waitcnt vmcnt(12)
	v_pk_fma_f32 v[60:61], v[60:61], v[120:121], v[214:215]
	v_pk_fma_f32 v[62:63], v[62:63], v[122:123], v[216:217]
	v_pk_fma_f32 v[56:57], v[56:57], v[112:113], v[218:219]
	v_pk_fma_f32 v[58:59], v[58:59], v[114:115], v[220:221]
	v_pk_fma_f32 v[52:53], v[52:53], v[108:109], v[222:223]
	v_pk_fma_f32 v[54:55], v[54:55], v[110:111], v[224:225]
	v_pk_fma_f32 v[48:49], v[48:49], v[104:105], v[226:227]
	v_pk_fma_f32 v[50:51], v[50:51], v[106:107], v[228:229]
	s_add_u32 s84, s80, 0x160000
	s_addc_u32 s85, s81, 0
	global_load_dwordx4 v[214:217], v173, s[84:85] nt
	global_load_dwordx4 v[218:221], v173, s[84:85] offset:16 nt
	global_load_dwordx4 v[222:225], v173, s[84:85] offset:512 nt
	global_load_dwordx4 v[226:229], v173, s[84:85] offset:528 nt
	v_pk_mul_f32 v[176:177], v[60:61], v[60:61]
	v_pk_fma_f32 v[176:177], v[62:63], v[62:63], v[176:177]
	v_pk_fma_f32 v[176:177], v[56:57], v[56:57], v[176:177]
	v_pk_fma_f32 v[176:177], v[58:59], v[58:59], v[176:177]
	v_pk_fma_f32 v[176:177], v[52:53], v[52:53], v[176:177]
	v_pk_fma_f32 v[176:177], v[54:55], v[54:55], v[176:177]
	v_pk_fma_f32 v[176:177], v[48:49], v[48:49], v[176:177]
	v_pk_fma_f32 v[176:177], v[50:51], v[50:51], v[176:177]
	v_add_f32_e32 v208, v176, v177
	s_waitcnt vmcnt(12)
	v_pk_fma_f32 v[44:45], v[44:45], v[120:121], v[230:231]
	v_pk_fma_f32 v[46:47], v[46:47], v[122:123], v[232:233]
	v_pk_fma_f32 v[40:41], v[40:41], v[112:113], v[234:235]
	v_pk_fma_f32 v[42:43], v[42:43], v[114:115], v[236:237]
	v_pk_fma_f32 v[36:37], v[36:37], v[108:109], v[238:239]
	v_pk_fma_f32 v[38:39], v[38:39], v[110:111], v[240:241]
	v_pk_fma_f32 v[32:33], v[32:33], v[104:105], v[242:243]
	v_pk_fma_f32 v[34:35], v[34:35], v[106:107], v[244:245]
	v_pk_mul_f32 v[176:177], v[44:45], v[44:45]
	v_pk_fma_f32 v[176:177], v[46:47], v[46:47], v[176:177]
	v_pk_fma_f32 v[176:177], v[40:41], v[40:41], v[176:177]
	v_pk_fma_f32 v[176:177], v[42:43], v[42:43], v[176:177]
	v_pk_fma_f32 v[176:177], v[36:37], v[36:37], v[176:177]
	v_pk_fma_f32 v[176:177], v[38:39], v[38:39], v[176:177]
	v_pk_fma_f32 v[176:177], v[32:33], v[32:33], v[176:177]
	v_pk_fma_f32 v[176:177], v[34:35], v[34:35], v[176:177]
	v_add_f32_e32 v209, v176, v177
	s_waitcnt vmcnt(4)
	v_pk_fma_f32 v[28:29], v[28:29], v[120:121], v[188:189]
	v_pk_fma_f32 v[30:31], v[30:31], v[122:123], v[190:191]
	v_pk_fma_f32 v[24:25], v[24:25], v[112:113], v[192:193]
	v_pk_fma_f32 v[26:27], v[26:27], v[114:115], v[194:195]
	v_pk_fma_f32 v[20:21], v[20:21], v[108:109], v[196:197]
	v_pk_fma_f32 v[22:23], v[22:23], v[110:111], v[198:199]
	v_pk_fma_f32 v[16:17], v[16:17], v[104:105], v[200:201]
	v_pk_fma_f32 v[18:19], v[18:19], v[106:107], v[202:203]
	v_pk_mul_f32 v[176:177], v[28:29], v[28:29]
	v_pk_fma_f32 v[176:177], v[30:31], v[30:31], v[176:177]
	v_pk_fma_f32 v[176:177], v[24:25], v[24:25], v[176:177]
	v_pk_fma_f32 v[176:177], v[26:27], v[26:27], v[176:177]
	v_pk_fma_f32 v[176:177], v[20:21], v[20:21], v[176:177]
	v_pk_fma_f32 v[176:177], v[22:23], v[22:23], v[176:177]
	v_pk_fma_f32 v[176:177], v[16:17], v[16:17], v[176:177]
	v_pk_fma_f32 v[176:177], v[18:19], v[18:19], v[176:177]
	v_add_f32_e32 v210, v176, v177
	s_barrier
	s_cmp_lg_u32 s59, 0
	s_cbranch_scc1 .Lepi_a1
	s_lshl_b32 s18, s58, 6
	s_add_u32 s18, s18, 0xc000
	s_mov_b64 exec, 1
	v_mov_b32_e32 v175, s18
	v_mov_b32_e32 v255, 1
	global_atomic_add v175, v255, s[50:51]
	s_mov_b64 exec, -1
.Lepi_a1:
	s_waitcnt vmcnt(0)
	v_pk_fma_f32 v[12:13], v[12:13], v[120:121], v[214:215]
	v_pk_fma_f32 v[14:15], v[14:15], v[122:123], v[216:217]
	v_pk_fma_f32 v[8:9], v[8:9], v[112:113], v[218:219]
	v_pk_fma_f32 v[10:11], v[10:11], v[114:115], v[220:221]
	v_pk_fma_f32 v[4:5], v[4:5], v[108:109], v[222:223]
	v_pk_fma_f32 v[6:7], v[6:7], v[110:111], v[224:225]
	v_pk_fma_f32 v[0:1], v[0:1], v[104:105], v[226:227]
	v_pk_fma_f32 v[2:3], v[2:3], v[106:107], v[228:229]
	v_pk_mul_f32 v[176:177], v[12:13], v[12:13]
	v_pk_fma_f32 v[176:177], v[14:15], v[14:15], v[176:177]
	v_pk_fma_f32 v[176:177], v[8:9], v[8:9], v[176:177]
	v_pk_fma_f32 v[176:177], v[10:11], v[10:11], v[176:177]
	v_pk_fma_f32 v[176:177], v[4:5], v[4:5], v[176:177]
	v_pk_fma_f32 v[176:177], v[6:7], v[6:7], v[176:177]
	v_pk_fma_f32 v[176:177], v[0:1], v[0:1], v[176:177]
	v_pk_fma_f32 v[176:177], v[2:3], v[2:3], v[176:177]
	v_add_f32_e32 v211, v176, v177
	s_cmp_lg_u32 s59, 0
	s_cbranch_scc1 .Lepi_b1
	s_waitcnt vmcnt(0)
	s_lshl_b32 s18, s58, 6
	s_add_u32 s18, s18, 0xc000
	s_mov_b64 exec, 1
	v_mov_b32_e32 v175, s18
	s_mov_b32 vcc_lo, 0

;     __device__ __forceinline__ void operator()(AccRef acc, const Unit& u, int wr, int wc, int fr, int fq) const {
;     ...
;                     ss += __shfl_xor(ss, 16); ss += __shfl_xor(ss, 32);
;                     if (fq == 0) rowss[(size_t)row * 32 + u.pn * 4 + wc] = ss; } }
; __device__ __forceinline__ void final_rows(int gw, int lane, const f16* xo, float* out, const float* fg, const float* rowss) {
;     ...
;         for (int rr = 0; rr < 4; ++rr) { part[rr] = lane < 32 ? rowss[(size_t)(r0 + rr) * 32 + lane] : 0.f;
; #pragma unroll
;             for (int j = 0; j < 4; ++j) v[rr][j] = *(const u32x4*)(xo + (size_t)(r0 + rr) * D + 512 * j + 8 * lane); }
;         __builtin_amdgcn_sched_barrier(0);
; #pragma unroll
;         for (int rr = 0; rr < 4; ++rr) { const float rstd = rsqrtf(wave_sum(part[rr]) * (1.f / D) + EPS); float* rp = out + (size_t)(r0 + rr) * D + 8 * lane;
.Lepi_b1:
	ds_bpermute_b32 v250, v186, v208
	ds_bpermute_b32 v251, v186, v209
	ds_bpermute_b32 v252, v186, v210
	ds_bpermute_b32 v253, v186, v211
	s_waitcnt lgkmcnt(0)
	v_pk_add_f32 v[208:209], v[208:209], v[250:251]
	v_pk_add_f32 v[210:211], v[210:211], v[252:253]
	ds_bpermute_b32 v250, v185, v208
	ds_bpermute_b32 v251, v185, v209
	ds_bpermute_b32 v252, v185, v210
	ds_bpermute_b32 v253, v185, v211
	s_waitcnt lgkmcnt(0)
	v_pk_add_f32 v[208:209], v[208:209], v[250:251]
	v_pk_add_f32 v[210:211], v[210:211], v[252:253]
	s_and_saveexec_b64 s[20:21], s[2:3]
	s_add_u32 s90, s88, 0x4000
	s_addc_u32 s91, s89, 0
	global_store_dword v187, v208, s[90:91] sc0 sc1
	s_add_u32 s90, s88, 0x4800
	s_addc_u32 s91, s89, 0
	global_store_dword v187, v209, s[90:91] sc0 sc1
	s_add_u32 s90, s88, 0x5000
	s_addc_u32 s91, s89, 0
	global_store_dword v187, v210, s[90:91] sc0 sc1
	s_add_u32 s90, s88, 0x5800
	s_addc_u32 s91, s89, 0
	global_store_dword v187, v211, s[90:91] sc0 sc1
	s_or_b64 exec, exec, s[20:21]
	s_barrier
	s_mov_b64 s[90:91], s[26:27]
	global_load_dwordx4 v[188:191], v174, s[90:91]
	global_load_dwordx4 v[192:195], v174, s[90:91] offset:16
	s_add_u32 s90, s26, 0x800
	s_addc_u32 s91, s27, 0
	global_load_dwordx4 v[196:199], v174, s[90:91]
	global_load_dwordx4 v[200:203], v174, s[90:91] offset:16
	s_add_u32 s90, s26, 0x1000
	s_addc_u32 s91, s27, 0
	global_load_dwordx4 v[214:217], v174, s[90:91]
	global_load_dwordx4 v[218:221], v174, s[90:91] offset:16
	s_add_u32 s90, s26, 0x1800
	s_addc_u32 s91, s27, 0
	global_load_dwordx4 v[222:225], v174, s[90:91]
	global_load_dwordx4 v[226:229], v174, s[90:91] offset:16
	s_waitcnt vmcnt(8)
	s_barrier
	s_cmp_lg_u32 s59, 0
	s_cbranch_scc1 .Lepi_c1
	s_lshl_b32 s18, s58, 6
	s_add_u32 s18, s18, 0xc020
	s_mov_b64 exec, 1
	v_mov_b32_e32 v175, s18
	v_mov_b32_e32 v255, 1
	global_atomic_add v175, v255, s[50:51]
	s_mov_b64 exec, -1
.Lepi_c1:
	s_waitcnt vmcnt(0)
	v_pk_add_f32 v[188:189], v[188:189], v[190:191]
	v_pk_add_f32 v[192:193], v[192:193], v[194:195]
	v_pk_add_f32 v[188:189], v[188:189], v[192:193]
	v_add_f32_e32 v188, v188, v189
	v_pk_add_f32 v[196:197], v[196:197], v[198:199]
	v_pk_add_f32 v[200:201], v[200:201], v[202:203]
	v_pk_add_f32 v[196:197], v[196:197], v[200:201]
	v_add_f32_e32 v196, v196, v197
	v_pk_add_f32 v[214:215], v[214:215], v[216:217]
	v_pk_add_f32 v[218:219], v[218:219], v[220:221]
	v_pk_add_f32 v[214:215], v[214:215], v[218:219]
	v_add_f32_e32 v214, v214, v215
	v_pk_add_f32 v[222:223], v[222:223], v[224:225]
	v_pk_add_f32 v[226:227], v[226:227], v[228:229]
	v_pk_add_f32 v[222:223], v[222:223], v[226:227]
	v_add_f32_e32 v222, v222, v223
	ds_bpermute_b32 v104, v186, v188
	ds_bpermute_b32 v105, v186, v196
	ds_bpermute_b32 v106, v186, v214
	ds_bpermute_b32 v107, v186, v222
	s_waitcnt lgkmcnt(0)
	v_add_f32_e32 v188, v188, v104
	v_add_f32_e32 v196, v196, v105
	v_add_f32_e32 v214, v214, v106
	v_add_f32_e32 v222, v222, v107
	ds_bpermute_b32 v104, v185, v188
	ds_bpermute_b32 v105, v185, v196
	ds_bpermute_b32 v106, v185, v214
	ds_bpermute_b32 v107, v185, v222
	s_waitcnt lgkmcnt(0)
	v_add_f32_e32 v188, v188, v104
	v_add_f32_e32 v196, v196, v105
	v_add_f32_e32 v214, v214, v106
	v_add_f32_e32 v222, v222, v107
	v_mov_b32_e32 v104, s95
	v_mov_b32_e32 v105, s95
	v_mov_b32_e32 v106, s95
	v_mov_b32_e32 v107, s95
	v_fmac_f32_e32 v104, s94, v188
	v_fmac_f32_e32 v105, s94, v196
	v_fmac_f32_e32 v106, s94, v214
	v_fmac_f32_e32 v107, s94, v222
	v_rsq_f32_e32 v188, v104
	v_rsq_f32_e32 v196, v105
	v_rsq_f32_e32 v214, v106
	v_rsq_f32_e32 v222, v107
	s_nop 1
	s_cmp_lg_u32 s59, 0
	s_cbranch_scc1 .Lepi_d1
	s_waitcnt vmcnt(0)
	s_lshl_b32 s18, s58, 6
	s_add_u32 s18, s18, 0xc020
	s_mov_b64 exec, 1
	v_mov_b32_e32 v175, s18
	s_mov_b32 vcc_lo, 0

; __device__ __forceinline__ void unpack8h(const u32x4 w, f32x4& v0, f32x4& v1) { v0 = (f32x4){h16lo(w.x), h16hi(w.x), h16lo(w.y), h16hi(w.y)}; v1 = (f32x4){h16lo(w.z), h16hi(w.z), h16lo(w.w), h16hi(w.w)}; }
; __device__ __forceinline__ void final_rows(int gw, int lane, const f16* xo, float* out, const float* fg, const float* rowss) {
;     ...
;         for (int rr = 0; rr < 4; ++rr) { const float rstd = rsqrtf(wave_sum(part[rr]) * (1.f / D) + EPS); float* rp = out + (size_t)(r0 + rr) * D + 8 * lane;
; #pragma unroll
;             for (int j = 0; j < 4; ++j) { f32x4 a0, a1; unpack8h(v[rr][j], a0, a1); *(f32x4*)(rp + 512 * j) = a0 * rstd * g4[j][0]; *(f32x4*)(rp + 512 * j + 4) = a1 * rstd * g4[j][1]; } }
.Lepi_d1:
	s_barrier
	s_add_u32 s90, s26, 0x4000
	s_addc_u32 s91, s27, 0
	global_load_dwordx4 v[230:233], v174, s[90:91]
	global_load_dwordx4 v[234:237], v174, s[90:91] offset:16
	s_add_u32 s90, s26, 0x4800
	s_addc_u32 s91, s27, 0
	global_load_dwordx4 v[238:241], v174, s[90:91]
	global_load_dwordx4 v[242:245], v174, s[90:91] offset:16
	s_add_u32 s90, s26, 0x5000
	s_addc_u32 s91, s27, 0
	global_load_dwordx4 v[204:207], v174, s[90:91]
	global_load_dwordx4 v[208:211], v174, s[90:91] offset:16
	s_add_u32 s90, s26, 0x5800
	s_addc_u32 s91, s27, 0
	global_load_dwordx4 v[246:249], v174, s[90:91]
	global_load_dwordx4 v[250:253], v174, s[90:91] offset:16
	s_mov_b64 s[86:87], s[82:83]
	v_pk_mul_f32 v[140:141], v[140:141], v[188:189] op_sel_hi:[1,0]
	v_pk_mul_f32 v[142:143], v[142:143], v[188:189] op_sel_hi:[1,0]
	v_pk_mul_f32 v[140:141], v[140:141], v[144:145]
	v_pk_mul_f32 v[142:143], v[142:143], v[146:147]
	v_pk_mul_f32 v[136:137], v[136:137], v[188:189] op_sel_hi:[1,0]
	v_pk_mul_f32 v[138:139], v[138:139], v[188:189] op_sel_hi:[1,0]
	v_pk_mul_f32 v[136:137], v[136:137], v[148:149]
	v_pk_mul_f32 v[138:139], v[138:139], v[150:151]
	v_pk_mul_f32 v[132:133], v[132:133], v[188:189] op_sel_hi:[1,0]
	v_pk_mul_f32 v[134:135], v[134:135], v[188:189] op_sel_hi:[1,0]
	v_pk_mul_f32 v[132:133], v[132:133], v[152:153]
	v_pk_mul_f32 v[134:135], v[134:135], v[154:155]
	v_pk_mul_f32 v[128:129], v[128:129], v[188:189] op_sel_hi:[1,0]
	v_pk_mul_f32 v[130:131], v[130:131], v[188:189] op_sel_hi:[1,0]
	v_pk_mul_f32 v[128:129], v[128:129], v[156:157]
	v_pk_mul_f32 v[130:131], v[130:131], v[158:159]
	global_store_dwordx4 v173, v[140:143], s[86:87]
	global_store_dwordx4 v173, v[136:139], s[86:87] offset:16
	global_store_dwordx4 v173, v[132:135], s[86:87] offset:512
	global_store_dwordx4 v173, v[128:131], s[86:87] offset:528
	s_add_u32 s86, s82, 0x20000
	s_addc_u32 s87, s83, 0
	v_pk_mul_f32 v[124:125], v[124:125], v[196:197] op_sel_hi:[1,0]
	v_pk_mul_f32 v[126:127], v[126:127], v[196:197] op_sel_hi:[1,0]
	v_pk_mul_f32 v[124:125], v[124:125], v[144:145]
	v_pk_mul_f32 v[126:127], v[126:127], v[146:147]
	v_pk_mul_f32 v[116:117], v[116:117], v[196:197] op_sel_hi:[1,0]
	v_pk_mul_f32 v[118:119], v[118:119], v[196:197] op_sel_hi:[1,0]
	v_pk_mul_f32 v[116:117], v[116:117], v[148:149]
	v_pk_mul_f32 v[118:119], v[118:119], v[150:151]
	v_pk_mul_f32 v[100:101], v[100:101], v[196:197] op_sel_hi:[1,0]
	v_pk_mul_f32 v[102:103], v[102:103], v[196:197] op_sel_hi:[1,0]
	v_pk_mul_f32 v[100:101], v[100:101], v[152:153]
	v_pk_mul_f32 v[102:103], v[102:103], v[154:155]
	v_pk_mul_f32 v[96:97], v[96:97], v[196:197] op_sel_hi:[1,0]
	v_pk_mul_f32 v[98:99], v[98:99], v[196:197] op_sel_hi:[1,0]
	v_pk_mul_f32 v[96:97], v[96:97], v[156:157]
	v_pk_mul_f32 v[98:99], v[98:99], v[158:159]
	global_store_dwordx4 v173, v[124:127], s[86:87]
	global_store_dwordx4 v173, v[116:119], s[86:87] offset:16
	global_store_dwordx4 v173, v[100:103], s[86:87] offset:512
	global_store_dwordx4 v173, v[96:99], s[86:87] offset:528
	s_add_u32 s86, s82, 0x40000
	s_addc_u32 s87, s83, 0
	v_pk_mul_f32 v[92:93], v[92:93], v[214:215] op_sel_hi:[1,0]
	v_pk_mul_f32 v[94:95], v[94:95], v[214:215] op_sel_hi:[1,0]
	v_pk_mul_f32 v[92:93], v[92:93], v[144:145]
	v_pk_mul_f32 v[94:95], v[94:95], v[146:147]
	v_pk_mul_f32 v[88:89], v[88:89], v[214:215] op_sel_hi:[1,0]
	v_pk_mul_f32 v[90:91], v[90:91], v[214:215] op_sel_hi:[1,0]
	v_pk_mul_f32 v[88:89], v[88:89], v[148:149]
	v_pk_mul_f32 v[90:91], v[90:91], v[150:151]
	v_pk_mul_f32 v[84:85], v[84:85], v[214:215] op_sel_hi:[1,0]
	v_pk_mul_f32 v[86:87], v[86:87], v[214:215] op_sel_hi:[1,0]
	v_pk_mul_f32 v[84:85], v[84:85], v[152:153]
	v_pk_mul_f32 v[86:87], v[86:87], v[154:155]
	v_pk_mul_f32 v[80:81], v[80:81], v[214:215] op_sel_hi:[1,0]
	v_pk_mul_f32 v[82:83], v[82:83], v[214:215] op_sel_hi:[1,0]
	v_pk_mul_f32 v[80:81], v[80:81], v[156:157]
	v_pk_mul_f32 v[82:83], v[82:83], v[158:159]
	global_store_dwordx4 v173, v[92:95], s[86:87]
	global_store_dwordx4 v173, v[88:91], s[86:87] offset:16
	global_store_dwordx4 v173, v[84:87], s[86:87] offset:512
	global_store_dwordx4 v173, v[80:83], s[86:87] offset:528
	s_add_u32 s86, s82, 0x60000
	s_addc_u32 s87, s83, 0
	v_pk_mul_f32 v[76:77], v[76:77], v[222:223] op_sel_hi:[1,0]
	v_pk_mul_f32 v[78:79], v[78:79], v[222:223] op_sel_hi:[1,0]
	v_pk_mul_f32 v[76:77], v[76:77], v[144:145]
	v_pk_mul_f32 v[78:79], v[78:79], v[146:147]
	v_pk_mul_f32 v[72:73], v[72:73], v[222:223] op_sel_hi:[1,0]
	v_pk_mul_f32 v[74:75], v[74:75], v[222:223] op_sel_hi:[1,0]
	v_pk_mul_f32 v[72:73], v[72:73], v[148:149]
	v_pk_mul_f32 v[74:75], v[74:75], v[150:151]
	v_pk_mul_f32 v[68:69], v[68:69], v[222:223] op_sel_hi:[1,0]
	v_pk_mul_f32 v[70:71], v[70:71], v[222:223] op_sel_hi:[1,0]
	v_pk_mul_f32 v[68:69], v[68:69], v[152:153]
	v_pk_mul_f32 v[70:71], v[70:71], v[154:155]
	v_pk_mul_f32 v[64:65], v[64:65], v[222:223] op_sel_hi:[1,0]
	v_pk_mul_f32 v[66:67], v[66:67], v[222:223] op_sel_hi:[1,0]
	v_pk_mul_f32 v[64:65], v[64:65], v[156:157]
	v_pk_mul_f32 v[66:67], v[66:67], v[158:159]
	global_store_dwordx4 v173, v[76:79], s[86:87]
	global_store_dwordx4 v173, v[72:75], s[86:87] offset:16
	global_store_dwordx4 v173, v[68:71], s[86:87] offset:512
	global_store_dwordx4 v173, v[64:67], s[86:87] offset:528
	s_waitcnt vmcnt(16)
; __device__ __forceinline__ void unpack8h(const u32x4 w, f32x4& v0, f32x4& v1) { v0 = (f32x4){h16lo(w.x), h16hi(w.x), h16lo(w.y), h16hi(w.y)}; v1 = (f32x4){h16lo(w.z), h16hi(w.z), h16lo(w.w), h16hi(w.w)}; }
; __device__ __forceinline__ void final_rows(int gw, int lane, const f16* xo, float* out, const float* fg, const float* rowss) {
;     ...
;         for (int rr = 0; rr < 4; ++rr) { const float rstd = rsqrtf(wave_sum(part[rr]) * (1.f / D) + EPS); float* rp = out + (size_t)(r0 + rr) * D + 8 * lane;
; #pragma unroll
;             for (int j = 0; j < 4; ++j) { f32x4 a0, a1; unpack8h(v[rr][j], a0, a1); *(f32x4*)(rp + 512 * j) = a0 * rstd * g4[j][0]; *(f32x4*)(rp + 512 * j + 4) = a1 * rstd * g4[j][1]; } }
	v_pk_add_f32 v[230:231], v[230:231], v[232:233]
	v_pk_add_f32 v[234:235], v[234:235], v[236:237]
	v_pk_add_f32 v[230:231], v[230:231], v[234:235]
	v_add_f32_e32 v230, v230, v231
	v_pk_add_f32 v[238:239], v[238:239], v[240:241]
	v_pk_add_f32 v[242:243], v[242:243], v[244:245]
	v_pk_add_f32 v[238:239], v[238:239], v[242:243]
	v_add_f32_e32 v238, v238, v239
	v_pk_add_f32 v[204:205], v[204:205], v[206:207]
	v_pk_add_f32 v[208:209], v[208:209], v[210:211]
	v_pk_add_f32 v[204:205], v[204:205], v[208:209]
	v_add_f32_e32 v204, v204, v205
	v_pk_add_f32 v[246:247], v[246:247], v[248:249]
	v_pk_add_f32 v[250:251], v[250:251], v[252:253]
	v_pk_add_f32 v[246:247], v[246:247], v[250:251]
	v_add_f32_e32 v246, v246, v247
	ds_bpermute_b32 v108, v186, v230
	ds_bpermute_b32 v109, v186, v238
	ds_bpermute_b32 v110, v186, v204
	ds_bpermute_b32 v111, v186, v246
	s_waitcnt lgkmcnt(0)
	v_add_f32_e32 v230, v230, v108
	v_add_f32_e32 v238, v238, v109
	v_add_f32_e32 v204, v204, v110
	v_add_f32_e32 v246, v246, v111
	ds_bpermute_b32 v108, v185, v230
	ds_bpermute_b32 v109, v185, v238
	ds_bpermute_b32 v110, v185, v204
	ds_bpermute_b32 v111, v185, v246
	s_waitcnt lgkmcnt(0)
	v_add_f32_e32 v230, v230, v108
	v_add_f32_e32 v238, v238, v109
	v_add_f32_e32 v204, v204, v110
	v_add_f32_e32 v246, v246, v111
	v_mov_b32_e32 v108, s95
	v_mov_b32_e32 v109, s95
	v_mov_b32_e32 v110, s95
	v_mov_b32_e32 v111, s95
	v_fmac_f32_e32 v108, s94, v230
	v_fmac_f32_e32 v109, s94, v238
	v_fmac_f32_e32 v110, s94, v204
	v_fmac_f32_e32 v111, s94, v246
	v_rsq_f32_e32 v230, v108
	v_rsq_f32_e32 v238, v109
	v_rsq_f32_e32 v204, v110
	v_rsq_f32_e32 v246, v111
	s_nop 1
	s_add_u32 s86, s82, 0x100000
	s_addc_u32 s87, s83, 0
	v_pk_mul_f32 v[60:61], v[60:61], v[230:231] op_sel_hi:[1,0]
	v_pk_mul_f32 v[62:63], v[62:63], v[230:231] op_sel_hi:[1,0]
	v_pk_mul_f32 v[60:61], v[60:61], v[144:145]
	v_pk_mul_f32 v[62:63], v[62:63], v[146:147]
	v_pk_mul_f32 v[56:57], v[56:57], v[230:231] op_sel_hi:[1,0]
	v_pk_mul_f32 v[58:59], v[58:59], v[230:231] op_sel_hi:[1,0]
	v_pk_mul_f32 v[56:57], v[56:57], v[148:149]
	v_pk_mul_f32 v[58:59], v[58:59], v[150:151]
	v_pk_mul_f32 v[52:53], v[52:53], v[230:231] op_sel_hi:[1,0]
	v_pk_mul_f32 v[54:55], v[54:55], v[230:231] op_sel_hi:[1,0]
	v_pk_mul_f32 v[52:53], v[52:53], v[152:153]
	v_pk_mul_f32 v[54:55], v[54:55], v[154:155]
	v_pk_mul_f32 v[48:49], v[48:49], v[230:231] op_sel_hi:[1,0]
	v_pk_mul_f32 v[50:51], v[50:51], v[230:231] op_sel_hi:[1,0]
	v_pk_mul_f32 v[48:49], v[48:49], v[156:157]
	v_pk_mul_f32 v[50:51], v[50:51], v[158:159]
	global_store_dwordx4 v173, v[60:63], s[86:87]
	global_store_dwordx4 v173, v[56:59], s[86:87] offset:16
	global_store_dwordx4 v173, v[52:55], s[86:87] offset:512
	global_store_dwordx4 v173, v[48:51], s[86:87] offset:528
	s_add_u32 s86, s82, 0x120000
	s_addc_u32 s87, s83, 0
	v_pk_mul_f32 v[44:45], v[44:45], v[238:239] op_sel_hi:[1,0]
	v_pk_mul_f32 v[46:47], v[46:47], v[238:239] op_sel_hi:[1,0]
	v_pk_mul_f32 v[44:45], v[44:45], v[144:145]
	v_pk_mul_f32 v[46:47], v[46:47], v[146:147]
	v_pk_mul_f32 v[40:41], v[40:41], v[238:239] op_sel_hi:[1,0]
	v_pk_mul_f32 v[42:43], v[42:43], v[238:239] op_sel_hi:[1,0]
	v_pk_mul_f32 v[40:41], v[40:41], v[148:149]
	v_pk_mul_f32 v[42:43], v[42:43], v[150:151]
	v_pk_mul_f32 v[36:37], v[36:37], v[238:239] op_sel_hi:[1,0]
	v_pk_mul_f32 v[38:39], v[38:39], v[238:239] op_sel_hi:[1,0]
	v_pk_mul_f32 v[36:37], v[36:37], v[152:153]
	v_pk_mul_f32 v[38:39], v[38:39], v[154:155]
	v_pk_mul_f32 v[32:33], v[32:33], v[238:239] op_sel_hi:[1,0]
	v_pk_mul_f32 v[34:35], v[34:35], v[238:239] op_sel_hi:[1,0]
	v_pk_mul_f32 v[32:33], v[32:33], v[156:157]
	v_pk_mul_f32 v[34:35], v[34:35], v[158:159]
	global_store_dwordx4 v173, v[44:47], s[86:87]
	global_store_dwordx4 v173, v[40:43], s[86:87] offset:16
	global_store_dwordx4 v173, v[36:39], s[86:87] offset:512
	global_store_dwordx4 v173, v[32:35], s[86:87] offset:528
	s_add_u32 s86, s82, 0x140000
	s_addc_u32 s87, s83, 0
	v_pk_mul_f32 v[28:29], v[28:29], v[204:205] op_sel_hi:[1,0]
	v_pk_mul_f32 v[30:31], v[30:31], v[204:205] op_sel_hi:[1,0]
	v_pk_mul_f32 v[28:29], v[28:29], v[144:145]
	v_pk_mul_f32 v[30:31], v[30:31], v[146:147]
	v_pk_mul_f32 v[24:25], v[24:25], v[204:205] op_sel_hi:[1,0]
	v_pk_mul_f32 v[26:27], v[26:27], v[204:205] op_sel_hi:[1,0]
	v_pk_mul_f32 v[24:25], v[24:25], v[148:149]
	v_pk_mul_f32 v[26:27], v[26:27], v[150:151]
	v_pk_mul_f32 v[20:21], v[20:21], v[204:205] op_sel_hi:[1,0]
	v_pk_mul_f32 v[22:23], v[22:23], v[204:205] op_sel_hi:[1,0]
	v_pk_mul_f32 v[20:21], v[20:21], v[152:153]
	v_pk_mul_f32 v[22:23], v[22:23], v[154:155]
	v_pk_mul_f32 v[16:17], v[16:17], v[204:205] op_sel_hi:[1,0]
	v_pk_mul_f32 v[18:19], v[18:19], v[204:205] op_sel_hi:[1,0]
	v_pk_mul_f32 v[16:17], v[16:17], v[156:157]
	v_pk_mul_f32 v[18:19], v[18:19], v[158:159]
	global_store_dwordx4 v173, v[28:31], s[86:87]
	global_store_dwordx4 v173, v[24:27], s[86:87] offset:16
	global_store_dwordx4 v173, v[20:23], s[86:87] offset:512
	global_store_dwordx4 v173, v[16:19], s[86:87] offset:528
	s_add_u32 s86, s82, 0x160000
	s_addc_u32 s87, s83, 0
	v_pk_mul_f32 v[12:13], v[12:13], v[246:247] op_sel_hi:[1,0]
	v_pk_mul_f32 v[14:15], v[14:15], v[246:247] op_sel_hi:[1,0]
	v_pk_mul_f32 v[12:13], v[12:13], v[144:145]
	v_pk_mul_f32 v[14:15], v[14:15], v[146:147]
	v_pk_mul_f32 v[8:9], v[8:9], v[246:247] op_sel_hi:[1,0]
	v_pk_mul_f32 v[10:11], v[10:11], v[246:247] op_sel_hi:[1,0]
	v_pk_mul_f32 v[8:9], v[8:9], v[148:149]
	v_pk_mul_f32 v[10:11], v[10:11], v[150:151]
	v_pk_mul_f32 v[4:5], v[4:5], v[246:247] op_sel_hi:[1,0]
	v_pk_mul_f32 v[6:7], v[6:7], v[246:247] op_sel_hi:[1,0]
	v_pk_mul_f32 v[4:5], v[4:5], v[152:153]
	v_pk_mul_f32 v[6:7], v[6:7], v[154:155]
	v_pk_mul_f32 v[0:1], v[0:1], v[246:247] op_sel_hi:[1,0]
	v_pk_mul_f32 v[2:3], v[2:3], v[246:247] op_sel_hi:[1,0]
	v_pk_mul_f32 v[0:1], v[0:1], v[156:157]
	v_pk_mul_f32 v[2:3], v[2:3], v[158:159]
	global_store_dwordx4 v173, v[12:15], s[86:87]
	global_store_dwordx4 v173, v[8:11], s[86:87] offset:16
	global_store_dwordx4 v173, v[4:7], s[86:87] offset:512
	global_store_dwordx4 v173, v[0:3], s[86:87] offset:528
	s_andn2_b64 vcc, exec, s[4:5]
	s_mov_b64 s[4:5], -1
	s_cbranch_vccnz .LBB0_1143
	s_andn2_b64 vcc, exec, s[14:15]
	s_cbranch_vccnz .LBB0_1142
	s_barrier
	s_branch .LBB0_1142
